# scan inner loop regenerated: 4 worker waves x 2 rows per lane with packed f32 FMAs (half the LDS operand reads), other 4 waves prepare the next chunk; scan workgroups skip the GEMM queue
# speedup vs baseline: 1.0107x; 1.0107x over previous
; #define LAS __attribute__((address_space(3)))
; #define LDS_WAIT() asm volatile("s_waitcnt lgkmcnt(0)" ::: "memory")
; __device__ __forceinline__ void scan_store(const ScanRegs& g, const ScanConst& K, const Args& A, LAS float* buf, int b, int h, int half, int c, int tid) {
;     const int jq = tid & 15, tl = tid >> 4, t = c * SC_TC + tl; const size_t m = (size_t)b * T + t;
;     const f32x4 mu_r = K.mu_r, mu_k = K.mu_k, kk_w = K.kk_w, ka_w = K.ka_w, rk_w = K.rk_w; const float mu_va = K.mu_va, mu_vb = K.mu_vb;
;     const f32x4 rs = g.r0 + (g.r1 - g.r0) * mu_r, ks = g.k0 + (g.k1 - g.k0) * mu_k;
;     f32x4 kk = ks * kk_w;
;     const float ss = row16_sum((kk.x * kk.x + kk.y * kk.y) + (kk.z * kk.z + kk.w * kk.w));
;     kk = kk * __builtin_amdgcn_rsqf(fmaxf(ss, 1e-24f));
;     const f32x4 km = ks * (1.0f + (g.al - 1.0f) * ka_w);
;     const f32x4 rkk = rs * km * rk_w;
;     const float cf = row16_sum((rkk.x + rkk.y) + (rkk.z + rkk.w));
;     if (half == 0 && jq == 0) ((float*)(A.ws + WS_COEF))[m * NH + h] = cf;
;     const f32x4 gt = g.e * g.w;
;     f32x4 inv; inv.x = __builtin_amdgcn_rcpf(gt.x); inv.y = __builtin_amdgcn_rcpf(gt.y); inv.z = __builtin_amdgcn_rcpf(gt.z); inv.w = __builtin_amdgcn_rcpf(gt.w);
;     LAS float* st = buf + tl * SC_STEP_F + 4 * jq;
;     *(LAS f32x4*)(st) = -(kk * g.e); *(LAS f32x4*)(st + 64) = kk * g.al * inv; *(LAS f32x4*)(st + 128) = km * inv; *(LAS f32x4*)(st + 192) = rs * gt;
;     if (tl == SC_TC - 1) *(LAS f32x4*)(buf + SC_G_OFF + 4 * jq) = gt;
;     buf[SC_V_OFF + tl * 32 + jq] = g.v0a + (g.v1a - g.v0a) * mu_va; buf[SC_V_OFF + tl * 32 + jq + 16] = g.v0b + (g.v1b - g.v0b) * mu_vb;
; }
; __device__ __forceinline__ void scan_unit(const Args& A, LAS unsigned char* lds, int s, int tid) {
;     ...
;     float S0 = 0.f, S1 = 0.f, S2 = 0.f, S3 = 0.f;
;     ScanRegs g; ScanConst K;
;     { const float* mu = A.in[4]; const int col = h * HD + 4 * jq, vcol = h * HD + 32 * half + jq;
;       K.mu_r = *(const f32x4*)(mu + col); K.mu_k = *(const f32x4*)(mu + RW + col); K.kk_w = *(const f32x4*)(A.in[9] + col); K.ka_w = *(const f32x4*)(A.in[10] + col); K.rk_w = *(const f32x4*)(A.in[11] + col);
;       K.mu_va = mu[2 * RW + vcol]; K.mu_vb = mu[2 * RW + vcol + 16]; }
;     scan_load(g, A.ws, b, h, half, 0, tid); scan_store(g, K, A, buf0, b, h, half, 0, tid);
;     LDS_WAIT(); __builtin_amdgcn_s_barrier(); asm volatile("" ::: "memory");
.LBB0_495:
	s_or_b64 exec, exec, s[16:17]
	v_add_f32_e32 v28, v28, v55
	v_max_f32_e32 v28, 0x179abe15, v28
	v_rsq_f32_e32 v28, v28
	s_waitcnt vmcnt(2)
	v_pk_mul_f32 v[54:55], v[42:43], v[50:51]
	v_pk_mul_f32 v[52:53], v[40:41], v[48:49]
	v_rcp_f32_e32 v88, v54
	v_rcp_f32_e32 v86, v52
	v_rcp_f32_e32 v87, v53
	v_rcp_f32_e32 v89, v55
	s_waitcnt vmcnt(1)
	v_pk_mul_f32 v[68:69], v[68:69], v[28:29] op_sel_hi:[1,0]
	v_pk_mul_f32 v[84:85], v[70:71], v[28:29] op_sel_hi:[1,0]
	v_lshlrev_b32_e32 v70, 10, v64
	v_lshlrev_b32_e32 v71, 2, v72
	v_xor_b32_e32 v81, 0x80000000, v51
	v_xor_b32_e32 v80, 0x80000000, v50
	v_add3_u32 v28, 0, v70, v71
	v_pk_mul_f32 v[82:83], v[68:69], v[80:81]
	v_pk_mul_f32 v[80:81], v[84:85], v[48:49] neg_lo:[0,1] neg_hi:[0,1]
	ds_write_b128 v28, v[80:83]
	v_pk_mul_f32 v[68:69], v[46:47], v[68:69]
	v_pk_mul_f32 v[80:81], v[44:45], v[84:85]
	s_mov_b32 s9, 0
	v_pk_mul_f32 v[82:83], v[88:89], v[68:69]
	v_pk_mul_f32 v[80:81], v[86:87], v[80:81]
	v_pk_mul_f32 v[68:69], v[58:59], v[88:89]
	v_pk_mul_f32 v[66:67], v[66:67], v[86:87]
	v_pk_mul_f32 v[58:59], v[30:31], v[54:55]
	v_pk_mul_f32 v[56:57], v[56:57], v[52:53]
	v_cmp_eq_u32_e64 s[4:5], 31, v64
	ds_write_b128 v28, v[80:83] offset:256
	ds_write_b128 v28, v[66:69] offset:512
	ds_write_b128 v28, v[56:59] offset:768
	s_and_saveexec_b64 s[16:17], s[4:5]
	v_lshl_add_u32 v28, v72, 2, 0
	ds_write_b128 v28, v[52:55] offset:36864
	s_or_b64 exec, exec, s[16:17]
	s_ashr_i32 s1, s1, 6
	s_mul_i32 s7, s1, 0x2200
	v_lshlrev_b32_e32 v80, 7, v64
	s_add_i32 s7, s7, 0
	v_sub_f32_e32 v30, v29, v75
	v_add3_u32 v31, 0, v80, v72
	s_waitcnt vmcnt(0)
	v_sub_f32_e32 v52, v77, v76
	v_and_b32_e32 v28, 63, v78
	s_add_i32 s7, s7, 0x12200
	v_fma_f32 v30, v73, v30, v75
	v_fma_f32 v52, v74, v52, v76
	v_add_u32_e32 v31, 0x8000, v31
	ds_write2_b32 v31, v30, v52 offset1:16
	v_lshl_add_u32 v81, v28, 2, s7
	v_and_b32_e32 v28, 31, v78
	v_and_b32_e32 v31, 32, v78
	v_mul_u32_u24_e32 v30, 0x110, v28
	v_lshlrev_b32_e32 v31, 2, v31
	s_lshl_b32 s18, s1, 2
	v_add3_u32 v82, s7, v30, v31
	s_mul_hi_u32 s1, s6, 0x1800000
	v_mul_hi_u32_u24_e32 v30, 0x1800, v28
	s_mul_i32 s7, s6, 0x1800000
	v_mul_u32_u24_e32 v28, 0x1800, v28
	v_or_b32_e32 v31, s1, v30
	v_lshrrev_b32_e32 v30, 2, v78
	s_ashr_i32 s19, s18, 31
	v_or_b32_e32 v28, s7, v28
	s_lshl_b32 s0, s0, 7
	v_and_b32_e32 v30, 8, v30
	v_or3_b32 v30, v28, s0, v30
	s_lshl_b64 s[0:1], s[18:19], 2
	s_lshl_b64 s[16:17], s[8:9], 2
	s_add_u32 s7, s34, s16
	s_addc_u32 s8, s35, s17
	s_add_u32 s0, s7, s0
	s_addc_u32 s1, s8, s1
	s_movk_i32 s15, 0x1800
	v_lshl_add_u64 v[30:31], s[0:1], 0, v[30:31]
	s_mov_b64 s[0:1], 0x28900000
	v_lshl_add_u64 v[56:57], v[30:31], 0, s[0:1]
	s_lshl_b64 s[0:1], s[14:15], 1
	s_and_b32 s1, s1, 1
	s_and_b32 s0, s0, -4
	s_add_u32 s0, s34, s0
	s_mul_i32 s8, s6, 0x5ffa0
	s_addc_u32 s1, s35, s1
	s_mul_hi_u32 s7, s6, 0x5ffa0
	s_add_u32 s0, s0, s8
	s_addc_u32 s1, s1, s7
	s_movk_i32 s7, 0x60
	v_mov_b64_e32 v[30:31], s[0:1]
	v_mad_i64_i32 v[30:31], s[0:1], v64, s7, v[30:31]
	s_mov_b64 s[0:1], 0x2b900c00
	s_nop 0
	v_lshl_add_u64 v[58:59], v[30:31], 0, s[0:1]
	v_mad_i64_i32 v[30:31], s[0:1], v64, s15, 0
	v_mov_b32_e32 v28, 0x1800000
	s_waitcnt lgkmcnt(0)
	s_barrier
	v_mad_u64_u32 v[30:31], s[0:1], s6, v28, v[30:31]
	v_lshl_add_u64 v[52:53], v[60:61], 2, v[30:31]
	v_lshl_add_u64 v[30:31], v[62:63], 2, v[30:31]
	v_bfe_u32 v79, v78, 4, 2
	v_add_u32_e32 v78, 32, v64
	v_lshl_add_u64 v[60:61], s[34:35], 0, v[52:53]
	v_lshl_add_u64 v[62:63], s[34:35], 0, v[30:31]
	v_mov_b32_e32 v28, 0
	s_mov_b64 s[14:15], 0
	s_add_i32 s8, 0, 0x9100
	s_add_i32 s38, 0, 0x8000
	s_add_i32 s39, 0, 0x11100
	s_add_i32 s40, 0, 0x9000
	s_mov_b32 s41, 0x12100
	s_add_i32 s42, 0, 0x12100
	s_mov_b64 s[16:17], 0xc00
	s_lshl_b32 s43, s18, 2
	v_mov_b32_e32 v83, 0
	v_mov_b32_e32 v84, 0
	v_mov_b32_e32 v85, 0
	v_mov_b32_e32 v86, 0
	v_mov_b32_e32 v122, 0
	v_mov_b32_e32 v123, 0
	v_mov_b32_e32 v124, 0
	v_mov_b32_e32 v125, 0
	v_mov_b32_e32 v126, 0
	v_mov_b32_e32 v127, 0
	v_mov_b32_e32 v128, 0
	v_mov_b32_e32 v129, 0
	s_branch .LBB0_500

; #define LAS __attribute__((address_space(3)))
; #define LDS_WAIT() asm volatile("s_waitcnt lgkmcnt(0)" ::: "memory")
; __device__ __forceinline__ void scan_unit(const Args& A, LAS unsigned char* lds, int s, int tid) {
;     ...
;         {
;             LDS_WAIT();
;             const LAS f32x4* yp = (const LAS f32x4*)(yb + (lane & 31) * SC_YS + (lane >> 5) * 32);
;             f32x4 s0 = yp[0] + yp[1] + (yp[2] + yp[3]), s1 = yp[4] + yp[5] + (yp[6] + yp[7]);
;             f32x2s o = (f32x2s){(s0.x + s0.y) + (s0.z + s0.w), (s1.x + s1.y) + (s1.z + s1.w)};
;             *(f32x2s*)(Y + ((size_t)b * T + c * SC_TC + (lane & 31)) * RW + h * HD + 32 * half + wave * 4 + (lane >> 5) * 2) = o;
;         }
;         LDS_WAIT(); __builtin_amdgcn_s_barrier(); asm volatile("" ::: "memory");
.LBB0_499:
	s_waitcnt lgkmcnt(0)
	s_barrier
	ds_read_b128 v[52:55], v82
	ds_read_b128 v[64:67], v82 offset:16
	ds_read_b128 v[88:91], v82 offset:32
	ds_read_b128 v[92:95], v82 offset:48
	v_lshl_add_u64 v[58:59], v[58:59], 0, s[16:17]
	v_add_u32_e32 v78, 32, v78
	s_waitcnt lgkmcnt(2)
	v_pk_add_f32 v[30:31], v[54:55], v[66:67]
	v_pk_add_f32 v[68:69], v[52:53], v[64:65]
	s_waitcnt lgkmcnt(0)
	v_pk_add_f32 v[96:97], v[90:91], v[94:95]
	v_pk_add_f32 v[98:99], v[88:89], v[92:93]
	ds_read_b128 v[52:55], v82 offset:64
	ds_read_b128 v[64:67], v82 offset:80
	ds_read_b128 v[88:91], v82 offset:96
	ds_read_b128 v[92:95], v82 offset:112
	v_pk_add_f32 v[68:69], v[68:69], v[98:99]
	v_pk_add_f32 v[30:31], v[30:31], v[96:97]
	s_waitcnt lgkmcnt(2)
	v_pk_add_f32 v[54:55], v[54:55], v[66:67]
	v_pk_add_f32 v[52:53], v[52:53], v[64:65]
	s_waitcnt lgkmcnt(0)
	v_pk_add_f32 v[66:67], v[88:89], v[92:93]
	v_pk_add_f32 v[64:65], v[90:91], v[94:95]
	v_pk_add_f32 v[52:53], v[52:53], v[66:67]
	v_pk_add_f32 v[54:55], v[54:55], v[64:65]
	v_mov_b32_e32 v64, v68
	v_mov_b32_e32 v65, v52
	v_mov_b32_e32 v52, v69
	v_pk_add_f32 v[52:53], v[64:65], v[52:53]
	v_mov_b32_e32 v64, v30
	v_mov_b32_e32 v65, v54
	v_mov_b32_e32 v54, v31
	v_pk_add_f32 v[30:31], v[64:65], v[54:55]
	s_nop 0
	v_pk_add_f32 v[30:31], v[52:53], v[30:31]
	v_lshl_add_u64 v[52:53], v[56:57], 0, s[14:15]
	global_store_dwordx2 v[52:53], v[30:31], off
	s_waitcnt lgkmcnt(0)
	s_barrier
	s_add_u32 s14, s14, 0x30000
	s_addc_u32 s15, s15, 0
	s_add_i32 s9, s9, 1
	s_cmp_eq_u32 s14, 0x1800000
	s_cbranch_scc1 .LBB0_511

; __device__ __forceinline__ void scan_unit(const Args& A, LAS unsigned char* lds, int s, int tid) {
;     ...
;     for (int c = 0; c < NCH; ++c) {
;         LAS float* cur = (c & 1) ? buf1 : buf0; LAS float* nxt = (c & 1) ? buf0 : buf1;
;         if (c + 1 < NCH) scan_load(g, A.ws, b, h, half, c + 1, tid);
;         {
;             const LAS float* st = cur + 4 * jq; const LAS float* vp = cur + SC_V_OFF + rl;
;             f32x4 a = *(const LAS f32x4*)(st), bb = *(const LAS f32x4*)(st + 64), k = *(const LAS f32x4*)(st + 128), r = *(const LAS f32x4*)(st + 192);
;             float v = vp[0];
;             f32x4 a1 = *(const LAS f32x4*)(st + SC_STEP_F), bb1 = *(const LAS f32x4*)(st + SC_STEP_F + 64), k1 = *(const LAS f32x4*)(st + SC_STEP_F + 128), r1 = *(const LAS f32x4*)(st + SC_STEP_F + 192);
;             float v1 = vp[32];
;             f32x4 pr = (f32x4){0.f, 0.f, 0.f, 0.f};
; #pragma unroll
;             for (int tl = 0; tl < SC_TC; ++tl) {
;                 float sa, yy;
;                 asm volatile(
;                     "v_mul_f32_e32 %0, %2, %6\n\t"
;                     "v_mul_f32_e32 %1, %2, %10\n\t"
;                     "v_fmac_f32_e32 %0, %3, %7\n\t"
;                     "v_fmac_f32_e32 %1, %3, %11\n\t"
;                     "v_fmac_f32_e32 %0, %4, %8\n\t"
;                     "v_fmac_f32_e32 %1, %4, %12\n\t"
;                     "v_fmac_f32_e32 %0, %5, %9\n\t"
;                     "v_fmac_f32_e32 %1, %5, %13\n\t"
;                     "v_fmac_f32_e32 %2, %18, %14\n\t"
;                     "v_add_f32_dpp %0, %0, %0 quad_perm:[1,0,3,2] row_mask:0xf bank_mask:0xf\n\t"
;                     "v_fmac_f32_e32 %3, %18, %15\n\t"
;                     "v_fmac_f32_e32 %4, %18, %16\n\t"
;                     "v_add_f32_dpp %0, %0, %0 quad_perm:[2,3,0,1] row_mask:0xf bank_mask:0xf\n\t"
;                     "v_fmac_f32_e32 %5, %18, %17\n\t"
;                     "s_nop 0\n\t"
;                     "v_add_f32_dpp %0, %0, %0 row_half_mirror row_mask:0xf bank_mask:0xf\n\t"
;                     : "=&v"(sa), "=&v"(yy), "+v"(S0), "+v"(S1), "+v"(S2), "+v"(S3)
;                     : "v"(a.x), "v"(a.y), "v"(a.z), "v"(a.w), "v"(pr.x), "v"(pr.y), "v"(pr.z), "v"(pr.w), "v"(k.x), "v"(k.y), "v"(k.z), "v"(k.w), "v"(v));
;                 if (tl > 0) yb[(tl - 1) * SC_YS + lane] = yy;
;                 const f32x4 b_now = bb; pr = r;
.LBB0_506:
	s_and_b32 s0, s9, 1
	s_cmp_eq_u32 s0, 0
	s_cselect_b64 s[6:7], -1, 0
	s_and_b64 s[0:1], s[6:7], exec
	s_cselect_b32 s0, 0, s8
	s_cselect_b32 s1, s38, s39
	v_add_u32_e32 v30, s0, v71
	s_cselect_b32 s0, s40, s42
	s_add_i32 s1, s1, s43
	v_lshl_add_u32 v31, v79, 2, s1
	s_cmp_gt_u32 s43, 63
	s_cbranch_scc1 .Lsc2_skip
	v_add_u32_e32 v31, s43, v31
	s_mul_i32 s1, s43, 0x220
	v_add_u32_e32 v204, s1, v81
	ds_read_b128 v[132:135], v30 offset:0
	ds_read_b128 v[136:139], v30 offset:256
	ds_read_b128 v[140:143], v30 offset:512
	ds_read_b128 v[144:147], v30 offset:768
	ds_read_b32 v148, v31 offset:0
	ds_read_b32 v149, v31 offset:16
	ds_read_b128 v[152:155], v30 offset:1024
	ds_read_b128 v[156:159], v30 offset:1280
	ds_read_b128 v[160:163], v30 offset:1536
	ds_read_b128 v[164:167], v30 offset:1792
	ds_read_b32 v168, v31 offset:128
	ds_read_b32 v169, v31 offset:144
	s_waitcnt lgkmcnt(11)
	v_pk_mul_f32 v[192:193], v[122:123], v[132:133]
	v_pk_mul_f32 v[194:195], v[126:127], v[132:133]
	v_pk_fma_f32 v[192:193], v[124:125], v[134:135], v[192:193]
	v_pk_fma_f32 v[194:195], v[128:129], v[134:135], v[194:195]
	v_add_f32_e32 v192, v192, v193
	v_add_f32_e32 v194, v194, v195
	s_waitcnt lgkmcnt(6)
	v_add_f32_dpp v192, v192, v192 quad_perm:[1,0,3,2] row_mask:0xf bank_mask:0xf
	v_add_f32_dpp v194, v194, v194 quad_perm:[1,0,3,2] row_mask:0xf bank_mask:0xf
	v_pk_fma_f32 v[122:123], v[148:149], v[140:141], v[122:123] op_sel_hi:[0,1,1]
	v_pk_fma_f32 v[126:127], v[148:149], v[140:141], v[126:127] op_sel:[1,0,0] op_sel_hi:[1,1,1]
	v_add_f32_dpp v192, v192, v192 quad_perm:[2,3,0,1] row_mask:0xf bank_mask:0xf
	v_add_f32_dpp v194, v194, v194 quad_perm:[2,3,0,1] row_mask:0xf bank_mask:0xf
	v_pk_fma_f32 v[124:125], v[148:149], v[142:143], v[124:125] op_sel_hi:[0,1,1]
	v_add_f32_dpp v192, v192, v192 row_half_mirror row_mask:0xf bank_mask:0xf
	v_add_f32_dpp v194, v194, v194 row_half_mirror row_mask:0xf bank_mask:0xf
	v_pk_fma_f32 v[128:129], v[148:149], v[142:143], v[128:129] op_sel:[1,0,0] op_sel_hi:[1,1,1]
	ds_read_b128 v[172:175], v30 offset:2048
	ds_read_b128 v[176:179], v30 offset:2304
	ds_read_b128 v[180:183], v30 offset:2560
	ds_read_b128 v[184:187], v30 offset:2816
	ds_read_b32 v188, v31 offset:256
	ds_read_b32 v189, v31 offset:272
	v_add_f32_dpp v192, v192, v192 row_mirror row_mask:0xf bank_mask:0xf
	v_add_f32_dpp v194, v194, v194 row_mirror row_mask:0xf bank_mask:0xf
	v_pk_fma_f32 v[122:123], v[192:193], v[136:137], v[122:123] op_sel_hi:[0,1,1]
	v_pk_fma_f32 v[126:127], v[194:195], v[136:137], v[126:127] op_sel_hi:[0,1,1]
	v_pk_fma_f32 v[124:125], v[192:193], v[138:139], v[124:125] op_sel_hi:[0,1,1]
	v_pk_fma_f32 v[128:129], v[194:195], v[138:139], v[128:129] op_sel_hi:[0,1,1]
	s_waitcnt lgkmcnt(11)
	v_pk_mul_f32 v[192:193], v[122:123], v[152:153]
	v_pk_mul_f32 v[194:195], v[126:127], v[152:153]
	v_pk_mul_f32 v[196:197], v[122:123], v[144:145]
	v_pk_mul_f32 v[198:199], v[126:127], v[144:145]
	v_pk_fma_f32 v[192:193], v[124:125], v[154:155], v[192:193]
	v_pk_fma_f32 v[194:195], v[128:129], v[154:155], v[194:195]
	v_pk_fma_f32 v[196:197], v[124:125], v[146:147], v[196:197]
	v_pk_fma_f32 v[198:199], v[128:129], v[146:147], v[198:199]
	v_add_f32_e32 v192, v192, v193
	v_add_f32_e32 v194, v194, v195
	v_add_f32_e32 v196, v196, v197
	v_add_f32_e32 v198, v198, v199
	s_waitcnt lgkmcnt(6)
	v_add_f32_dpp v192, v192, v192 quad_perm:[1,0,3,2] row_mask:0xf bank_mask:0xf
	v_add_f32_dpp v194, v194, v194 quad_perm:[1,0,3,2] row_mask:0xf bank_mask:0xf
	v_pk_fma_f32 v[122:123], v[168:169], v[160:161], v[122:123] op_sel_hi:[0,1,1]
	v_pk_fma_f32 v[126:127], v[168:169], v[160:161], v[126:127] op_sel:[1,0,0] op_sel_hi:[1,1,1]
	v_add_f32_dpp v192, v192, v192 quad_perm:[2,3,0,1] row_mask:0xf bank_mask:0xf
	v_add_f32_dpp v194, v194, v194 quad_perm:[2,3,0,1] row_mask:0xf bank_mask:0xf
	v_pk_fma_f32 v[124:125], v[168:169], v[162:163], v[124:125] op_sel_hi:[0,1,1]
	v_add_f32_dpp v192, v192, v192 row_half_mirror row_mask:0xf bank_mask:0xf
	v_add_f32_dpp v194, v194, v194 row_half_mirror row_mask:0xf bank_mask:0xf
	v_pk_fma_f32 v[128:129], v[168:169], v[162:163], v[128:129] op_sel:[1,0,0] op_sel_hi:[1,1,1]
	ds_write_b32 v204, v196 offset:0
	ds_write_b32 v204, v198 offset:8704
	ds_read_b128 v[132:135], v30 offset:3072
	ds_read_b128 v[136:139], v30 offset:3328
	ds_read_b128 v[140:143], v30 offset:3584
	ds_read_b128 v[144:147], v30 offset:3840
	ds_read_b32 v148, v31 offset:384
	ds_read_b32 v149, v31 offset:400
	v_add_f32_dpp v192, v192, v192 row_mirror row_mask:0xf bank_mask:0xf
	v_add_f32_dpp v194, v194, v194 row_mirror row_mask:0xf bank_mask:0xf
	v_pk_fma_f32 v[122:123], v[192:193], v[156:157], v[122:123] op_sel_hi:[0,1,1]
	v_pk_fma_f32 v[126:127], v[194:195], v[156:157], v[126:127] op_sel_hi:[0,1,1]
	v_pk_fma_f32 v[124:125], v[192:193], v[158:159], v[124:125] op_sel_hi:[0,1,1]
	v_pk_fma_f32 v[128:129], v[194:195], v[158:159], v[128:129] op_sel_hi:[0,1,1]
	s_waitcnt lgkmcnt(13)
	v_pk_mul_f32 v[192:193], v[122:123], v[172:173]
	v_pk_mul_f32 v[194:195], v[126:127], v[172:173]
	v_pk_mul_f32 v[196:197], v[122:123], v[164:165]
	v_pk_mul_f32 v[198:199], v[126:127], v[164:165]
	v_pk_fma_f32 v[192:193], v[124:125], v[174:175], v[192:193]
	v_pk_fma_f32 v[194:195], v[128:129], v[174:175], v[194:195]
	v_pk_fma_f32 v[196:197], v[124:125], v[166:167], v[196:197]
	v_pk_fma_f32 v[198:199], v[128:129], v[166:167], v[198:199]
	v_add_f32_e32 v192, v192, v193
	v_add_f32_e32 v194, v194, v195
	v_add_f32_e32 v196, v196, v197
	v_add_f32_e32 v198, v198, v199
	s_waitcnt lgkmcnt(8)
; __device__ __forceinline__ void scan_unit(const Args& A, LAS unsigned char* lds, int s, int tid) {
;     ...
;             for (int tl = 0; tl < SC_TC; ++tl) {
;                 float sa, yy;
;                 asm volatile(
;                     "v_mul_f32_e32 %0, %2, %6\n\t"
;                     "v_mul_f32_e32 %1, %2, %10\n\t"
;                     "v_fmac_f32_e32 %0, %3, %7\n\t"
;                     "v_fmac_f32_e32 %1, %3, %11\n\t"
;                     "v_fmac_f32_e32 %0, %4, %8\n\t"
;                     "v_fmac_f32_e32 %1, %4, %12\n\t"
;                     "v_fmac_f32_e32 %0, %5, %9\n\t"
;                     "v_fmac_f32_e32 %1, %5, %13\n\t"
;                     "v_fmac_f32_e32 %2, %18, %14\n\t"
;                     "v_add_f32_dpp %0, %0, %0 quad_perm:[1,0,3,2] row_mask:0xf bank_mask:0xf\n\t"
;                     "v_fmac_f32_e32 %3, %18, %15\n\t"
;                     "v_fmac_f32_e32 %4, %18, %16\n\t"
;                     "v_add_f32_dpp %0, %0, %0 quad_perm:[2,3,0,1] row_mask:0xf bank_mask:0xf\n\t"
;                     "v_fmac_f32_e32 %5, %18, %17\n\t"
;                     "s_nop 0\n\t"
;                     "v_add_f32_dpp %0, %0, %0 row_half_mirror row_mask:0xf bank_mask:0xf\n\t"
;                     : "=&v"(sa), "=&v"(yy), "+v"(S0), "+v"(S1), "+v"(S2), "+v"(S3)
;                     : "v"(a.x), "v"(a.y), "v"(a.z), "v"(a.w), "v"(pr.x), "v"(pr.y), "v"(pr.z), "v"(pr.w), "v"(k.x), "v"(k.y), "v"(k.z), "v"(k.w), "v"(v));
;                 if (tl > 0) yb[(tl - 1) * SC_YS + lane] = yy;
;                 const f32x4 b_now = bb; pr = r;
;                 a = a1; bb = bb1; k = k1; r = r1; v = v1;
;                 if (tl + 2 < SC_TC) { const LAS float* sn = st + (tl + 2) * SC_STEP_F;
;                     a1 = *(const LAS f32x4*)(sn); bb1 = *(const LAS f32x4*)(sn + 64); k1 = *(const LAS f32x4*)(sn + 128); r1 = *(const LAS f32x4*)(sn + 192); v1 = vp[(tl + 2) * 32]; }
;                 __builtin_amdgcn_sched_barrier(0);
;                 if (tl + 2 >= SC_TC) asm volatile("s_nop 1");
;                 asm volatile(
;                     "v_add_f32_dpp %4, %4, %4 row_mirror row_mask:0xf bank_mask:0xf\n\t"
;                     "v_fmac_f32_e32 %0, %4, %5\n\t"
;                     "v_fmac_f32_e32 %1, %4, %6\n\t"
;                     "v_fmac_f32_e32 %2, %4, %7\n\t"
;                     "v_fmac_f32_e32 %3, %4, %8\n\t"
	v_add_f32_dpp v192, v192, v192 quad_perm:[1,0,3,2] row_mask:0xf bank_mask:0xf
	v_add_f32_dpp v194, v194, v194 quad_perm:[1,0,3,2] row_mask:0xf bank_mask:0xf
	v_pk_fma_f32 v[122:123], v[188:189], v[180:181], v[122:123] op_sel_hi:[0,1,1]
	v_pk_fma_f32 v[126:127], v[188:189], v[180:181], v[126:127] op_sel:[1,0,0] op_sel_hi:[1,1,1]
	v_add_f32_dpp v192, v192, v192 quad_perm:[2,3,0,1] row_mask:0xf bank_mask:0xf
	v_add_f32_dpp v194, v194, v194 quad_perm:[2,3,0,1] row_mask:0xf bank_mask:0xf
	v_pk_fma_f32 v[124:125], v[188:189], v[182:183], v[124:125] op_sel_hi:[0,1,1]
	v_add_f32_dpp v192, v192, v192 row_half_mirror row_mask:0xf bank_mask:0xf
	v_add_f32_dpp v194, v194, v194 row_half_mirror row_mask:0xf bank_mask:0xf
	v_pk_fma_f32 v[128:129], v[188:189], v[182:183], v[128:129] op_sel:[1,0,0] op_sel_hi:[1,1,1]
	ds_write_b32 v204, v196 offset:272
	ds_write_b32 v204, v198 offset:8976
	ds_read_b128 v[152:155], v30 offset:4096
	ds_read_b128 v[156:159], v30 offset:4352
	ds_read_b128 v[160:163], v30 offset:4608
	ds_read_b128 v[164:167], v30 offset:4864
	ds_read_b32 v168, v31 offset:512
	ds_read_b32 v169, v31 offset:528
	v_add_f32_dpp v192, v192, v192 row_mirror row_mask:0xf bank_mask:0xf
	v_add_f32_dpp v194, v194, v194 row_mirror row_mask:0xf bank_mask:0xf
	v_pk_fma_f32 v[122:123], v[192:193], v[176:177], v[122:123] op_sel_hi:[0,1,1]
	v_pk_fma_f32 v[126:127], v[194:195], v[176:177], v[126:127] op_sel_hi:[0,1,1]
	v_pk_fma_f32 v[124:125], v[192:193], v[178:179], v[124:125] op_sel_hi:[0,1,1]
	v_pk_fma_f32 v[128:129], v[194:195], v[178:179], v[128:129] op_sel_hi:[0,1,1]
	s_waitcnt lgkmcnt(13)
	v_pk_mul_f32 v[192:193], v[122:123], v[132:133]
	v_pk_mul_f32 v[194:195], v[126:127], v[132:133]
	v_pk_mul_f32 v[196:197], v[122:123], v[184:185]
	v_pk_mul_f32 v[198:199], v[126:127], v[184:185]
	v_pk_fma_f32 v[192:193], v[124:125], v[134:135], v[192:193]
	v_pk_fma_f32 v[194:195], v[128:129], v[134:135], v[194:195]
	v_pk_fma_f32 v[196:197], v[124:125], v[186:187], v[196:197]
	v_pk_fma_f32 v[198:199], v[128:129], v[186:187], v[198:199]
	v_add_f32_e32 v192, v192, v193
	v_add_f32_e32 v194, v194, v195
	v_add_f32_e32 v196, v196, v197
	v_add_f32_e32 v198, v198, v199
	s_waitcnt lgkmcnt(8)
	v_add_f32_dpp v192, v192, v192 quad_perm:[1,0,3,2] row_mask:0xf bank_mask:0xf
	v_add_f32_dpp v194, v194, v194 quad_perm:[1,0,3,2] row_mask:0xf bank_mask:0xf
	v_pk_fma_f32 v[122:123], v[148:149], v[140:141], v[122:123] op_sel_hi:[0,1,1]
	v_pk_fma_f32 v[126:127], v[148:149], v[140:141], v[126:127] op_sel:[1,0,0] op_sel_hi:[1,1,1]
	v_add_f32_dpp v192, v192, v192 quad_perm:[2,3,0,1] row_mask:0xf bank_mask:0xf
	v_add_f32_dpp v194, v194, v194 quad_perm:[2,3,0,1] row_mask:0xf bank_mask:0xf
	v_pk_fma_f32 v[124:125], v[148:149], v[142:143], v[124:125] op_sel_hi:[0,1,1]
	v_add_f32_dpp v192, v192, v192 row_half_mirror row_mask:0xf bank_mask:0xf
	v_add_f32_dpp v194, v194, v194 row_half_mirror row_mask:0xf bank_mask:0xf
	v_pk_fma_f32 v[128:129], v[148:149], v[142:143], v[128:129] op_sel:[1,0,0] op_sel_hi:[1,1,1]
	ds_write_b32 v204, v196 offset:544
	ds_write_b32 v204, v198 offset:9248
	ds_read_b128 v[172:175], v30 offset:5120
	ds_read_b128 v[176:179], v30 offset:5376
	ds_read_b128 v[180:183], v30 offset:5632
	ds_read_b128 v[184:187], v30 offset:5888
	ds_read_b32 v188, v31 offset:640
	ds_read_b32 v189, v31 offset:656
	v_add_f32_dpp v192, v192, v192 row_mirror row_mask:0xf bank_mask:0xf
	v_add_f32_dpp v194, v194, v194 row_mirror row_mask:0xf bank_mask:0xf
	v_pk_fma_f32 v[122:123], v[192:193], v[136:137], v[122:123] op_sel_hi:[0,1,1]
	v_pk_fma_f32 v[126:127], v[194:195], v[136:137], v[126:127] op_sel_hi:[0,1,1]
	v_pk_fma_f32 v[124:125], v[192:193], v[138:139], v[124:125] op_sel_hi:[0,1,1]
	v_pk_fma_f32 v[128:129], v[194:195], v[138:139], v[128:129] op_sel_hi:[0,1,1]
	s_waitcnt lgkmcnt(13)
	v_pk_mul_f32 v[192:193], v[122:123], v[152:153]
	v_pk_mul_f32 v[194:195], v[126:127], v[152:153]
	v_pk_mul_f32 v[196:197], v[122:123], v[144:145]
	v_pk_mul_f32 v[198:199], v[126:127], v[144:145]
	v_pk_fma_f32 v[192:193], v[124:125], v[154:155], v[192:193]
	v_pk_fma_f32 v[194:195], v[128:129], v[154:155], v[194:195]
	v_pk_fma_f32 v[196:197], v[124:125], v[146:147], v[196:197]
	v_pk_fma_f32 v[198:199], v[128:129], v[146:147], v[198:199]
	v_add_f32_e32 v192, v192, v193
	v_add_f32_e32 v194, v194, v195
	v_add_f32_e32 v196, v196, v197
	v_add_f32_e32 v198, v198, v199
	s_waitcnt lgkmcnt(8)
	v_add_f32_dpp v192, v192, v192 quad_perm:[1,0,3,2] row_mask:0xf bank_mask:0xf
	v_add_f32_dpp v194, v194, v194 quad_perm:[1,0,3,2] row_mask:0xf bank_mask:0xf
	v_pk_fma_f32 v[122:123], v[168:169], v[160:161], v[122:123] op_sel_hi:[0,1,1]
	v_pk_fma_f32 v[126:127], v[168:169], v[160:161], v[126:127] op_sel:[1,0,0] op_sel_hi:[1,1,1]
	v_add_f32_dpp v192, v192, v192 quad_perm:[2,3,0,1] row_mask:0xf bank_mask:0xf
	v_add_f32_dpp v194, v194, v194 quad_perm:[2,3,0,1] row_mask:0xf bank_mask:0xf
	v_pk_fma_f32 v[124:125], v[168:169], v[162:163], v[124:125] op_sel_hi:[0,1,1]
	v_add_f32_dpp v192, v192, v192 row_half_mirror row_mask:0xf bank_mask:0xf
	v_add_f32_dpp v194, v194, v194 row_half_mirror row_mask:0xf bank_mask:0xf
	v_pk_fma_f32 v[128:129], v[168:169], v[162:163], v[128:129] op_sel:[1,0,0] op_sel_hi:[1,1,1]
	ds_write_b32 v204, v196 offset:816
	ds_write_b32 v204, v198 offset:9520
	ds_read_b128 v[132:135], v30 offset:6144
	ds_read_b128 v[136:139], v30 offset:6400
	ds_read_b128 v[140:143], v30 offset:6656
	ds_read_b128 v[144:147], v30 offset:6912
	ds_read_b32 v148, v31 offset:768
	ds_read_b32 v149, v31 offset:784
	v_add_f32_dpp v192, v192, v192 row_mirror row_mask:0xf bank_mask:0xf
	v_add_f32_dpp v194, v194, v194 row_mirror row_mask:0xf bank_mask:0xf
	v_pk_fma_f32 v[122:123], v[192:193], v[156:157], v[122:123] op_sel_hi:[0,1,1]
	v_pk_fma_f32 v[126:127], v[194:195], v[156:157], v[126:127] op_sel_hi:[0,1,1]
	v_pk_fma_f32 v[124:125], v[192:193], v[158:159], v[124:125] op_sel_hi:[0,1,1]
	v_pk_fma_f32 v[128:129], v[194:195], v[158:159], v[128:129] op_sel_hi:[0,1,1]
	s_waitcnt lgkmcnt(13)
; __device__ __forceinline__ void scan_unit(const Args& A, LAS unsigned char* lds, int s, int tid) {
;     ...
;             for (int tl = 0; tl < SC_TC; ++tl) {
;                 float sa, yy;
;                 asm volatile(
;                     "v_mul_f32_e32 %0, %2, %6\n\t"
;                     "v_mul_f32_e32 %1, %2, %10\n\t"
;                     "v_fmac_f32_e32 %0, %3, %7\n\t"
;                     "v_fmac_f32_e32 %1, %3, %11\n\t"
;                     "v_fmac_f32_e32 %0, %4, %8\n\t"
;                     "v_fmac_f32_e32 %1, %4, %12\n\t"
;                     "v_fmac_f32_e32 %0, %5, %9\n\t"
;                     "v_fmac_f32_e32 %1, %5, %13\n\t"
;                     "v_fmac_f32_e32 %2, %18, %14\n\t"
;                     "v_add_f32_dpp %0, %0, %0 quad_perm:[1,0,3,2] row_mask:0xf bank_mask:0xf\n\t"
;                     "v_fmac_f32_e32 %3, %18, %15\n\t"
;                     "v_fmac_f32_e32 %4, %18, %16\n\t"
;                     "v_add_f32_dpp %0, %0, %0 quad_perm:[2,3,0,1] row_mask:0xf bank_mask:0xf\n\t"
;                     "v_fmac_f32_e32 %5, %18, %17\n\t"
;                     "s_nop 0\n\t"
;                     "v_add_f32_dpp %0, %0, %0 row_half_mirror row_mask:0xf bank_mask:0xf\n\t"
;                     : "=&v"(sa), "=&v"(yy), "+v"(S0), "+v"(S1), "+v"(S2), "+v"(S3)
;                     : "v"(a.x), "v"(a.y), "v"(a.z), "v"(a.w), "v"(pr.x), "v"(pr.y), "v"(pr.z), "v"(pr.w), "v"(k.x), "v"(k.y), "v"(k.z), "v"(k.w), "v"(v));
;                 if (tl > 0) yb[(tl - 1) * SC_YS + lane] = yy;
;                 const f32x4 b_now = bb; pr = r;
;                 a = a1; bb = bb1; k = k1; r = r1; v = v1;
;                 if (tl + 2 < SC_TC) { const LAS float* sn = st + (tl + 2) * SC_STEP_F;
;                     a1 = *(const LAS f32x4*)(sn); bb1 = *(const LAS f32x4*)(sn + 64); k1 = *(const LAS f32x4*)(sn + 128); r1 = *(const LAS f32x4*)(sn + 192); v1 = vp[(tl + 2) * 32]; }
;                 __builtin_amdgcn_sched_barrier(0);
;                 if (tl + 2 >= SC_TC) asm volatile("s_nop 1");
;                 asm volatile(
;                     "v_add_f32_dpp %4, %4, %4 row_mirror row_mask:0xf bank_mask:0xf\n\t"
;                     "v_fmac_f32_e32 %0, %4, %5\n\t"
;                     "v_fmac_f32_e32 %1, %4, %6\n\t"
;                     "v_fmac_f32_e32 %2, %4, %7\n\t"
;                     "v_fmac_f32_e32 %3, %4, %8\n\t"
	v_pk_mul_f32 v[192:193], v[122:123], v[172:173]
	v_pk_mul_f32 v[194:195], v[126:127], v[172:173]
	v_pk_mul_f32 v[196:197], v[122:123], v[164:165]
	v_pk_mul_f32 v[198:199], v[126:127], v[164:165]
	v_pk_fma_f32 v[192:193], v[124:125], v[174:175], v[192:193]
	v_pk_fma_f32 v[194:195], v[128:129], v[174:175], v[194:195]
	v_pk_fma_f32 v[196:197], v[124:125], v[166:167], v[196:197]
	v_pk_fma_f32 v[198:199], v[128:129], v[166:167], v[198:199]
	v_add_f32_e32 v192, v192, v193
	v_add_f32_e32 v194, v194, v195
	v_add_f32_e32 v196, v196, v197
	v_add_f32_e32 v198, v198, v199
	s_waitcnt lgkmcnt(8)
	v_add_f32_dpp v192, v192, v192 quad_perm:[1,0,3,2] row_mask:0xf bank_mask:0xf
	v_add_f32_dpp v194, v194, v194 quad_perm:[1,0,3,2] row_mask:0xf bank_mask:0xf
	v_pk_fma_f32 v[122:123], v[188:189], v[180:181], v[122:123] op_sel_hi:[0,1,1]
	v_pk_fma_f32 v[126:127], v[188:189], v[180:181], v[126:127] op_sel:[1,0,0] op_sel_hi:[1,1,1]
	v_add_f32_dpp v192, v192, v192 quad_perm:[2,3,0,1] row_mask:0xf bank_mask:0xf
	v_add_f32_dpp v194, v194, v194 quad_perm:[2,3,0,1] row_mask:0xf bank_mask:0xf
	v_pk_fma_f32 v[124:125], v[188:189], v[182:183], v[124:125] op_sel_hi:[0,1,1]
	v_add_f32_dpp v192, v192, v192 row_half_mirror row_mask:0xf bank_mask:0xf
	v_add_f32_dpp v194, v194, v194 row_half_mirror row_mask:0xf bank_mask:0xf
	v_pk_fma_f32 v[128:129], v[188:189], v[182:183], v[128:129] op_sel:[1,0,0] op_sel_hi:[1,1,1]
	ds_write_b32 v204, v196 offset:1088
	ds_write_b32 v204, v198 offset:9792
	ds_read_b128 v[152:155], v30 offset:7168
	ds_read_b128 v[156:159], v30 offset:7424
	ds_read_b128 v[160:163], v30 offset:7680
	ds_read_b128 v[164:167], v30 offset:7936
	ds_read_b32 v168, v31 offset:896
	ds_read_b32 v169, v31 offset:912
	v_add_f32_dpp v192, v192, v192 row_mirror row_mask:0xf bank_mask:0xf
	v_add_f32_dpp v194, v194, v194 row_mirror row_mask:0xf bank_mask:0xf
	v_pk_fma_f32 v[122:123], v[192:193], v[176:177], v[122:123] op_sel_hi:[0,1,1]
	v_pk_fma_f32 v[126:127], v[194:195], v[176:177], v[126:127] op_sel_hi:[0,1,1]
	v_pk_fma_f32 v[124:125], v[192:193], v[178:179], v[124:125] op_sel_hi:[0,1,1]
	v_pk_fma_f32 v[128:129], v[194:195], v[178:179], v[128:129] op_sel_hi:[0,1,1]
	s_waitcnt lgkmcnt(13)
	v_pk_mul_f32 v[192:193], v[122:123], v[132:133]
	v_pk_mul_f32 v[194:195], v[126:127], v[132:133]
	v_pk_mul_f32 v[196:197], v[122:123], v[184:185]
	v_pk_mul_f32 v[198:199], v[126:127], v[184:185]
	v_pk_fma_f32 v[192:193], v[124:125], v[134:135], v[192:193]
	v_pk_fma_f32 v[194:195], v[128:129], v[134:135], v[194:195]
	v_pk_fma_f32 v[196:197], v[124:125], v[186:187], v[196:197]
	v_pk_fma_f32 v[198:199], v[128:129], v[186:187], v[198:199]
	v_add_f32_e32 v192, v192, v193
	v_add_f32_e32 v194, v194, v195
	v_add_f32_e32 v196, v196, v197
	v_add_f32_e32 v198, v198, v199
	s_waitcnt lgkmcnt(8)
	v_add_f32_dpp v192, v192, v192 quad_perm:[1,0,3,2] row_mask:0xf bank_mask:0xf
	v_add_f32_dpp v194, v194, v194 quad_perm:[1,0,3,2] row_mask:0xf bank_mask:0xf
	v_pk_fma_f32 v[122:123], v[148:149], v[140:141], v[122:123] op_sel_hi:[0,1,1]
	v_pk_fma_f32 v[126:127], v[148:149], v[140:141], v[126:127] op_sel:[1,0,0] op_sel_hi:[1,1,1]
	v_add_f32_dpp v192, v192, v192 quad_perm:[2,3,0,1] row_mask:0xf bank_mask:0xf
	v_add_f32_dpp v194, v194, v194 quad_perm:[2,3,0,1] row_mask:0xf bank_mask:0xf
	v_pk_fma_f32 v[124:125], v[148:149], v[142:143], v[124:125] op_sel_hi:[0,1,1]
	v_add_f32_dpp v192, v192, v192 row_half_mirror row_mask:0xf bank_mask:0xf
	v_add_f32_dpp v194, v194, v194 row_half_mirror row_mask:0xf bank_mask:0xf
	v_pk_fma_f32 v[128:129], v[148:149], v[142:143], v[128:129] op_sel:[1,0,0] op_sel_hi:[1,1,1]
	ds_write_b32 v204, v196 offset:1360
	ds_write_b32 v204, v198 offset:10064
	ds_read_b128 v[172:175], v30 offset:8192
	ds_read_b128 v[176:179], v30 offset:8448
	ds_read_b128 v[180:183], v30 offset:8704
	ds_read_b128 v[184:187], v30 offset:8960
	ds_read_b32 v188, v31 offset:1024
	ds_read_b32 v189, v31 offset:1040
	v_add_f32_dpp v192, v192, v192 row_mirror row_mask:0xf bank_mask:0xf
	v_add_f32_dpp v194, v194, v194 row_mirror row_mask:0xf bank_mask:0xf
	v_pk_fma_f32 v[122:123], v[192:193], v[136:137], v[122:123] op_sel_hi:[0,1,1]
	v_pk_fma_f32 v[126:127], v[194:195], v[136:137], v[126:127] op_sel_hi:[0,1,1]
	v_pk_fma_f32 v[124:125], v[192:193], v[138:139], v[124:125] op_sel_hi:[0,1,1]
	v_pk_fma_f32 v[128:129], v[194:195], v[138:139], v[128:129] op_sel_hi:[0,1,1]
	s_waitcnt lgkmcnt(13)
	v_pk_mul_f32 v[192:193], v[122:123], v[152:153]
	v_pk_mul_f32 v[194:195], v[126:127], v[152:153]
	v_pk_mul_f32 v[196:197], v[122:123], v[144:145]
	v_pk_mul_f32 v[198:199], v[126:127], v[144:145]
	v_pk_fma_f32 v[192:193], v[124:125], v[154:155], v[192:193]
	v_pk_fma_f32 v[194:195], v[128:129], v[154:155], v[194:195]
	v_pk_fma_f32 v[196:197], v[124:125], v[146:147], v[196:197]
	v_pk_fma_f32 v[198:199], v[128:129], v[146:147], v[198:199]
	v_add_f32_e32 v192, v192, v193
	v_add_f32_e32 v194, v194, v195
	v_add_f32_e32 v196, v196, v197
	v_add_f32_e32 v198, v198, v199
	s_waitcnt lgkmcnt(8)
; __device__ __forceinline__ void scan_unit(const Args& A, LAS unsigned char* lds, int s, int tid) {
;     ...
;             for (int tl = 0; tl < SC_TC; ++tl) {
;                 float sa, yy;
;                 asm volatile(
;                     "v_mul_f32_e32 %0, %2, %6\n\t"
;                     "v_mul_f32_e32 %1, %2, %10\n\t"
;                     "v_fmac_f32_e32 %0, %3, %7\n\t"
;                     "v_fmac_f32_e32 %1, %3, %11\n\t"
;                     "v_fmac_f32_e32 %0, %4, %8\n\t"
;                     "v_fmac_f32_e32 %1, %4, %12\n\t"
;                     "v_fmac_f32_e32 %0, %5, %9\n\t"
;                     "v_fmac_f32_e32 %1, %5, %13\n\t"
;                     "v_fmac_f32_e32 %2, %18, %14\n\t"
;                     "v_add_f32_dpp %0, %0, %0 quad_perm:[1,0,3,2] row_mask:0xf bank_mask:0xf\n\t"
;                     "v_fmac_f32_e32 %3, %18, %15\n\t"
;                     "v_fmac_f32_e32 %4, %18, %16\n\t"
;                     "v_add_f32_dpp %0, %0, %0 quad_perm:[2,3,0,1] row_mask:0xf bank_mask:0xf\n\t"
;                     "v_fmac_f32_e32 %5, %18, %17\n\t"
;                     "s_nop 0\n\t"
;                     "v_add_f32_dpp %0, %0, %0 row_half_mirror row_mask:0xf bank_mask:0xf\n\t"
;                     : "=&v"(sa), "=&v"(yy), "+v"(S0), "+v"(S1), "+v"(S2), "+v"(S3)
;                     : "v"(a.x), "v"(a.y), "v"(a.z), "v"(a.w), "v"(pr.x), "v"(pr.y), "v"(pr.z), "v"(pr.w), "v"(k.x), "v"(k.y), "v"(k.z), "v"(k.w), "v"(v));
;                 if (tl > 0) yb[(tl - 1) * SC_YS + lane] = yy;
;                 const f32x4 b_now = bb; pr = r;
;                 a = a1; bb = bb1; k = k1; r = r1; v = v1;
;                 if (tl + 2 < SC_TC) { const LAS float* sn = st + (tl + 2) * SC_STEP_F;
;                     a1 = *(const LAS f32x4*)(sn); bb1 = *(const LAS f32x4*)(sn + 64); k1 = *(const LAS f32x4*)(sn + 128); r1 = *(const LAS f32x4*)(sn + 192); v1 = vp[(tl + 2) * 32]; }
;                 __builtin_amdgcn_sched_barrier(0);
;                 if (tl + 2 >= SC_TC) asm volatile("s_nop 1");
;                 asm volatile(
;                     "v_add_f32_dpp %4, %4, %4 row_mirror row_mask:0xf bank_mask:0xf\n\t"
;                     "v_fmac_f32_e32 %0, %4, %5\n\t"
;                     "v_fmac_f32_e32 %1, %4, %6\n\t"
;                     "v_fmac_f32_e32 %2, %4, %7\n\t"
;                     "v_fmac_f32_e32 %3, %4, %8\n\t"
	v_add_f32_dpp v192, v192, v192 quad_perm:[1,0,3,2] row_mask:0xf bank_mask:0xf
	v_add_f32_dpp v194, v194, v194 quad_perm:[1,0,3,2] row_mask:0xf bank_mask:0xf
	v_pk_fma_f32 v[122:123], v[168:169], v[160:161], v[122:123] op_sel_hi:[0,1,1]
	v_pk_fma_f32 v[126:127], v[168:169], v[160:161], v[126:127] op_sel:[1,0,0] op_sel_hi:[1,1,1]
	v_add_f32_dpp v192, v192, v192 quad_perm:[2,3,0,1] row_mask:0xf bank_mask:0xf
	v_add_f32_dpp v194, v194, v194 quad_perm:[2,3,0,1] row_mask:0xf bank_mask:0xf
	v_pk_fma_f32 v[124:125], v[168:169], v[162:163], v[124:125] op_sel_hi:[0,1,1]
	v_add_f32_dpp v192, v192, v192 row_half_mirror row_mask:0xf bank_mask:0xf
	v_add_f32_dpp v194, v194, v194 row_half_mirror row_mask:0xf bank_mask:0xf
	v_pk_fma_f32 v[128:129], v[168:169], v[162:163], v[128:129] op_sel:[1,0,0] op_sel_hi:[1,1,1]
	ds_write_b32 v204, v196 offset:1632
	ds_write_b32 v204, v198 offset:10336
	ds_read_b128 v[132:135], v30 offset:9216
	ds_read_b128 v[136:139], v30 offset:9472
	ds_read_b128 v[140:143], v30 offset:9728
	ds_read_b128 v[144:147], v30 offset:9984
	ds_read_b32 v148, v31 offset:1152
	ds_read_b32 v149, v31 offset:1168
	v_add_f32_dpp v192, v192, v192 row_mirror row_mask:0xf bank_mask:0xf
	v_add_f32_dpp v194, v194, v194 row_mirror row_mask:0xf bank_mask:0xf
	v_pk_fma_f32 v[122:123], v[192:193], v[156:157], v[122:123] op_sel_hi:[0,1,1]
	v_pk_fma_f32 v[126:127], v[194:195], v[156:157], v[126:127] op_sel_hi:[0,1,1]
	v_pk_fma_f32 v[124:125], v[192:193], v[158:159], v[124:125] op_sel_hi:[0,1,1]
	v_pk_fma_f32 v[128:129], v[194:195], v[158:159], v[128:129] op_sel_hi:[0,1,1]
	s_waitcnt lgkmcnt(13)
	v_pk_mul_f32 v[192:193], v[122:123], v[172:173]
	v_pk_mul_f32 v[194:195], v[126:127], v[172:173]
	v_pk_mul_f32 v[196:197], v[122:123], v[164:165]
	v_pk_mul_f32 v[198:199], v[126:127], v[164:165]
	v_pk_fma_f32 v[192:193], v[124:125], v[174:175], v[192:193]
	v_pk_fma_f32 v[194:195], v[128:129], v[174:175], v[194:195]
	v_pk_fma_f32 v[196:197], v[124:125], v[166:167], v[196:197]
	v_pk_fma_f32 v[198:199], v[128:129], v[166:167], v[198:199]
	v_add_f32_e32 v192, v192, v193
	v_add_f32_e32 v194, v194, v195
	v_add_f32_e32 v196, v196, v197
	v_add_f32_e32 v198, v198, v199
	s_waitcnt lgkmcnt(8)
	v_add_f32_dpp v192, v192, v192 quad_perm:[1,0,3,2] row_mask:0xf bank_mask:0xf
	v_add_f32_dpp v194, v194, v194 quad_perm:[1,0,3,2] row_mask:0xf bank_mask:0xf
	v_pk_fma_f32 v[122:123], v[188:189], v[180:181], v[122:123] op_sel_hi:[0,1,1]
	v_pk_fma_f32 v[126:127], v[188:189], v[180:181], v[126:127] op_sel:[1,0,0] op_sel_hi:[1,1,1]
	v_add_f32_dpp v192, v192, v192 quad_perm:[2,3,0,1] row_mask:0xf bank_mask:0xf
	v_add_f32_dpp v194, v194, v194 quad_perm:[2,3,0,1] row_mask:0xf bank_mask:0xf
	v_pk_fma_f32 v[124:125], v[188:189], v[182:183], v[124:125] op_sel_hi:[0,1,1]
	v_add_f32_dpp v192, v192, v192 row_half_mirror row_mask:0xf bank_mask:0xf
	v_add_f32_dpp v194, v194, v194 row_half_mirror row_mask:0xf bank_mask:0xf
	v_pk_fma_f32 v[128:129], v[188:189], v[182:183], v[128:129] op_sel:[1,0,0] op_sel_hi:[1,1,1]
	ds_write_b32 v204, v196 offset:1904
	ds_write_b32 v204, v198 offset:10608
	ds_read_b128 v[152:155], v30 offset:10240
	ds_read_b128 v[156:159], v30 offset:10496
	ds_read_b128 v[160:163], v30 offset:10752
	ds_read_b128 v[164:167], v30 offset:11008
	ds_read_b32 v168, v31 offset:1280
	ds_read_b32 v169, v31 offset:1296
	v_add_f32_dpp v192, v192, v192 row_mirror row_mask:0xf bank_mask:0xf
	v_add_f32_dpp v194, v194, v194 row_mirror row_mask:0xf bank_mask:0xf
	v_pk_fma_f32 v[122:123], v[192:193], v[176:177], v[122:123] op_sel_hi:[0,1,1]
	v_pk_fma_f32 v[126:127], v[194:195], v[176:177], v[126:127] op_sel_hi:[0,1,1]
	v_pk_fma_f32 v[124:125], v[192:193], v[178:179], v[124:125] op_sel_hi:[0,1,1]
	v_pk_fma_f32 v[128:129], v[194:195], v[178:179], v[128:129] op_sel_hi:[0,1,1]
	s_waitcnt lgkmcnt(13)
	v_pk_mul_f32 v[192:193], v[122:123], v[132:133]
	v_pk_mul_f32 v[194:195], v[126:127], v[132:133]
	v_pk_mul_f32 v[196:197], v[122:123], v[184:185]
	v_pk_mul_f32 v[198:199], v[126:127], v[184:185]
	v_pk_fma_f32 v[192:193], v[124:125], v[134:135], v[192:193]
	v_pk_fma_f32 v[194:195], v[128:129], v[134:135], v[194:195]
	v_pk_fma_f32 v[196:197], v[124:125], v[186:187], v[196:197]
	v_pk_fma_f32 v[198:199], v[128:129], v[186:187], v[198:199]
	v_add_f32_e32 v192, v192, v193
	v_add_f32_e32 v194, v194, v195
	v_add_f32_e32 v196, v196, v197
	v_add_f32_e32 v198, v198, v199
	s_waitcnt lgkmcnt(8)
	v_add_f32_dpp v192, v192, v192 quad_perm:[1,0,3,2] row_mask:0xf bank_mask:0xf
	v_add_f32_dpp v194, v194, v194 quad_perm:[1,0,3,2] row_mask:0xf bank_mask:0xf
	v_pk_fma_f32 v[122:123], v[148:149], v[140:141], v[122:123] op_sel_hi:[0,1,1]
	v_pk_fma_f32 v[126:127], v[148:149], v[140:141], v[126:127] op_sel:[1,0,0] op_sel_hi:[1,1,1]
	v_add_f32_dpp v192, v192, v192 quad_perm:[2,3,0,1] row_mask:0xf bank_mask:0xf
	v_add_f32_dpp v194, v194, v194 quad_perm:[2,3,0,1] row_mask:0xf bank_mask:0xf
	v_pk_fma_f32 v[124:125], v[148:149], v[142:143], v[124:125] op_sel_hi:[0,1,1]
	v_add_f32_dpp v192, v192, v192 row_half_mirror row_mask:0xf bank_mask:0xf
	v_add_f32_dpp v194, v194, v194 row_half_mirror row_mask:0xf bank_mask:0xf
	v_pk_fma_f32 v[128:129], v[148:149], v[142:143], v[128:129] op_sel:[1,0,0] op_sel_hi:[1,1,1]
	ds_write_b32 v204, v196 offset:2176
	ds_write_b32 v204, v198 offset:10880
	ds_read_b128 v[172:175], v30 offset:11264
	ds_read_b128 v[176:179], v30 offset:11520
	ds_read_b128 v[180:183], v30 offset:11776
	ds_read_b128 v[184:187], v30 offset:12032
	ds_read_b32 v188, v31 offset:1408
	ds_read_b32 v189, v31 offset:1424
	v_add_f32_dpp v192, v192, v192 row_mirror row_mask:0xf bank_mask:0xf
	v_add_f32_dpp v194, v194, v194 row_mirror row_mask:0xf bank_mask:0xf
	v_pk_fma_f32 v[122:123], v[192:193], v[136:137], v[122:123] op_sel_hi:[0,1,1]
	v_pk_fma_f32 v[126:127], v[194:195], v[136:137], v[126:127] op_sel_hi:[0,1,1]
	v_pk_fma_f32 v[124:125], v[192:193], v[138:139], v[124:125] op_sel_hi:[0,1,1]
	v_pk_fma_f32 v[128:129], v[194:195], v[138:139], v[128:129] op_sel_hi:[0,1,1]
	s_waitcnt lgkmcnt(13)
; __device__ __forceinline__ void scan_unit(const Args& A, LAS unsigned char* lds, int s, int tid) {
;     ...
;             for (int tl = 0; tl < SC_TC; ++tl) {
;                 float sa, yy;
;                 asm volatile(
;                     "v_mul_f32_e32 %0, %2, %6\n\t"
;                     "v_mul_f32_e32 %1, %2, %10\n\t"
;                     "v_fmac_f32_e32 %0, %3, %7\n\t"
;                     "v_fmac_f32_e32 %1, %3, %11\n\t"
;                     "v_fmac_f32_e32 %0, %4, %8\n\t"
;                     "v_fmac_f32_e32 %1, %4, %12\n\t"
;                     "v_fmac_f32_e32 %0, %5, %9\n\t"
;                     "v_fmac_f32_e32 %1, %5, %13\n\t"
;                     "v_fmac_f32_e32 %2, %18, %14\n\t"
;                     "v_add_f32_dpp %0, %0, %0 quad_perm:[1,0,3,2] row_mask:0xf bank_mask:0xf\n\t"
;                     "v_fmac_f32_e32 %3, %18, %15\n\t"
;                     "v_fmac_f32_e32 %4, %18, %16\n\t"
;                     "v_add_f32_dpp %0, %0, %0 quad_perm:[2,3,0,1] row_mask:0xf bank_mask:0xf\n\t"
;                     "v_fmac_f32_e32 %5, %18, %17\n\t"
;                     "s_nop 0\n\t"
;                     "v_add_f32_dpp %0, %0, %0 row_half_mirror row_mask:0xf bank_mask:0xf\n\t"
;                     : "=&v"(sa), "=&v"(yy), "+v"(S0), "+v"(S1), "+v"(S2), "+v"(S3)
;                     : "v"(a.x), "v"(a.y), "v"(a.z), "v"(a.w), "v"(pr.x), "v"(pr.y), "v"(pr.z), "v"(pr.w), "v"(k.x), "v"(k.y), "v"(k.z), "v"(k.w), "v"(v));
;                 if (tl > 0) yb[(tl - 1) * SC_YS + lane] = yy;
;                 const f32x4 b_now = bb; pr = r;
;                 a = a1; bb = bb1; k = k1; r = r1; v = v1;
;                 if (tl + 2 < SC_TC) { const LAS float* sn = st + (tl + 2) * SC_STEP_F;
;                     a1 = *(const LAS f32x4*)(sn); bb1 = *(const LAS f32x4*)(sn + 64); k1 = *(const LAS f32x4*)(sn + 128); r1 = *(const LAS f32x4*)(sn + 192); v1 = vp[(tl + 2) * 32]; }
;                 __builtin_amdgcn_sched_barrier(0);
;                 if (tl + 2 >= SC_TC) asm volatile("s_nop 1");
;                 asm volatile(
;                     "v_add_f32_dpp %4, %4, %4 row_mirror row_mask:0xf bank_mask:0xf\n\t"
;                     "v_fmac_f32_e32 %0, %4, %5\n\t"
;                     "v_fmac_f32_e32 %1, %4, %6\n\t"
;                     "v_fmac_f32_e32 %2, %4, %7\n\t"
;                     "v_fmac_f32_e32 %3, %4, %8\n\t"
	v_pk_mul_f32 v[192:193], v[122:123], v[152:153]
	v_pk_mul_f32 v[194:195], v[126:127], v[152:153]
	v_pk_mul_f32 v[196:197], v[122:123], v[144:145]
	v_pk_mul_f32 v[198:199], v[126:127], v[144:145]
	v_pk_fma_f32 v[192:193], v[124:125], v[154:155], v[192:193]
	v_pk_fma_f32 v[194:195], v[128:129], v[154:155], v[194:195]
	v_pk_fma_f32 v[196:197], v[124:125], v[146:147], v[196:197]
	v_pk_fma_f32 v[198:199], v[128:129], v[146:147], v[198:199]
	v_add_f32_e32 v192, v192, v193
	v_add_f32_e32 v194, v194, v195
	v_add_f32_e32 v196, v196, v197
	v_add_f32_e32 v198, v198, v199
	s_waitcnt lgkmcnt(8)
	v_add_f32_dpp v192, v192, v192 quad_perm:[1,0,3,2] row_mask:0xf bank_mask:0xf
	v_add_f32_dpp v194, v194, v194 quad_perm:[1,0,3,2] row_mask:0xf bank_mask:0xf
	v_pk_fma_f32 v[122:123], v[168:169], v[160:161], v[122:123] op_sel_hi:[0,1,1]
	v_pk_fma_f32 v[126:127], v[168:169], v[160:161], v[126:127] op_sel:[1,0,0] op_sel_hi:[1,1,1]
	v_add_f32_dpp v192, v192, v192 quad_perm:[2,3,0,1] row_mask:0xf bank_mask:0xf
	v_add_f32_dpp v194, v194, v194 quad_perm:[2,3,0,1] row_mask:0xf bank_mask:0xf
	v_pk_fma_f32 v[124:125], v[168:169], v[162:163], v[124:125] op_sel_hi:[0,1,1]
	v_add_f32_dpp v192, v192, v192 row_half_mirror row_mask:0xf bank_mask:0xf
	v_add_f32_dpp v194, v194, v194 row_half_mirror row_mask:0xf bank_mask:0xf
	v_pk_fma_f32 v[128:129], v[168:169], v[162:163], v[128:129] op_sel:[1,0,0] op_sel_hi:[1,1,1]
	ds_write_b32 v204, v196 offset:2448
	ds_write_b32 v204, v198 offset:11152
	ds_read_b128 v[132:135], v30 offset:12288
	ds_read_b128 v[136:139], v30 offset:12544
	ds_read_b128 v[140:143], v30 offset:12800
	ds_read_b128 v[144:147], v30 offset:13056
	ds_read_b32 v148, v31 offset:1536
	ds_read_b32 v149, v31 offset:1552
	v_add_f32_dpp v192, v192, v192 row_mirror row_mask:0xf bank_mask:0xf
	v_add_f32_dpp v194, v194, v194 row_mirror row_mask:0xf bank_mask:0xf
	v_pk_fma_f32 v[122:123], v[192:193], v[156:157], v[122:123] op_sel_hi:[0,1,1]
	v_pk_fma_f32 v[126:127], v[194:195], v[156:157], v[126:127] op_sel_hi:[0,1,1]
	v_pk_fma_f32 v[124:125], v[192:193], v[158:159], v[124:125] op_sel_hi:[0,1,1]
	v_pk_fma_f32 v[128:129], v[194:195], v[158:159], v[128:129] op_sel_hi:[0,1,1]
	s_waitcnt lgkmcnt(13)
	v_pk_mul_f32 v[192:193], v[122:123], v[172:173]
	v_pk_mul_f32 v[194:195], v[126:127], v[172:173]
	v_pk_mul_f32 v[196:197], v[122:123], v[164:165]
	v_pk_mul_f32 v[198:199], v[126:127], v[164:165]
	v_pk_fma_f32 v[192:193], v[124:125], v[174:175], v[192:193]
	v_pk_fma_f32 v[194:195], v[128:129], v[174:175], v[194:195]
	v_pk_fma_f32 v[196:197], v[124:125], v[166:167], v[196:197]
	v_pk_fma_f32 v[198:199], v[128:129], v[166:167], v[198:199]
	v_add_f32_e32 v192, v192, v193
	v_add_f32_e32 v194, v194, v195
	v_add_f32_e32 v196, v196, v197
	v_add_f32_e32 v198, v198, v199
	s_waitcnt lgkmcnt(8)
	v_add_f32_dpp v192, v192, v192 quad_perm:[1,0,3,2] row_mask:0xf bank_mask:0xf
	v_add_f32_dpp v194, v194, v194 quad_perm:[1,0,3,2] row_mask:0xf bank_mask:0xf
	v_pk_fma_f32 v[122:123], v[188:189], v[180:181], v[122:123] op_sel_hi:[0,1,1]
	v_pk_fma_f32 v[126:127], v[188:189], v[180:181], v[126:127] op_sel:[1,0,0] op_sel_hi:[1,1,1]
	v_add_f32_dpp v192, v192, v192 quad_perm:[2,3,0,1] row_mask:0xf bank_mask:0xf
	v_add_f32_dpp v194, v194, v194 quad_perm:[2,3,0,1] row_mask:0xf bank_mask:0xf
	v_pk_fma_f32 v[124:125], v[188:189], v[182:183], v[124:125] op_sel_hi:[0,1,1]
	v_add_f32_dpp v192, v192, v192 row_half_mirror row_mask:0xf bank_mask:0xf
	v_add_f32_dpp v194, v194, v194 row_half_mirror row_mask:0xf bank_mask:0xf
	v_pk_fma_f32 v[128:129], v[188:189], v[182:183], v[128:129] op_sel:[1,0,0] op_sel_hi:[1,1,1]
	ds_write_b32 v204, v196 offset:2720
	ds_write_b32 v204, v198 offset:11424
	ds_read_b128 v[152:155], v30 offset:13312
	ds_read_b128 v[156:159], v30 offset:13568
	ds_read_b128 v[160:163], v30 offset:13824
	ds_read_b128 v[164:167], v30 offset:14080
	ds_read_b32 v168, v31 offset:1664
	ds_read_b32 v169, v31 offset:1680
	v_add_f32_dpp v192, v192, v192 row_mirror row_mask:0xf bank_mask:0xf
	v_add_f32_dpp v194, v194, v194 row_mirror row_mask:0xf bank_mask:0xf
	v_pk_fma_f32 v[122:123], v[192:193], v[176:177], v[122:123] op_sel_hi:[0,1,1]
	v_pk_fma_f32 v[126:127], v[194:195], v[176:177], v[126:127] op_sel_hi:[0,1,1]
	v_pk_fma_f32 v[124:125], v[192:193], v[178:179], v[124:125] op_sel_hi:[0,1,1]
	v_pk_fma_f32 v[128:129], v[194:195], v[178:179], v[128:129] op_sel_hi:[0,1,1]
	s_waitcnt lgkmcnt(13)
	v_pk_mul_f32 v[192:193], v[122:123], v[132:133]
	v_pk_mul_f32 v[194:195], v[126:127], v[132:133]
	v_pk_mul_f32 v[196:197], v[122:123], v[184:185]
	v_pk_mul_f32 v[198:199], v[126:127], v[184:185]
	v_pk_fma_f32 v[192:193], v[124:125], v[134:135], v[192:193]
	v_pk_fma_f32 v[194:195], v[128:129], v[134:135], v[194:195]
	v_pk_fma_f32 v[196:197], v[124:125], v[186:187], v[196:197]
	v_pk_fma_f32 v[198:199], v[128:129], v[186:187], v[198:199]
	v_add_f32_e32 v192, v192, v193
	v_add_f32_e32 v194, v194, v195
	v_add_f32_e32 v196, v196, v197
	v_add_f32_e32 v198, v198, v199
	s_waitcnt lgkmcnt(8)
; __device__ __forceinline__ void scan_unit(const Args& A, LAS unsigned char* lds, int s, int tid) {
;     ...
;             for (int tl = 0; tl < SC_TC; ++tl) {
;                 float sa, yy;
;                 asm volatile(
;                     "v_mul_f32_e32 %0, %2, %6\n\t"
;                     "v_mul_f32_e32 %1, %2, %10\n\t"
;                     "v_fmac_f32_e32 %0, %3, %7\n\t"
;                     "v_fmac_f32_e32 %1, %3, %11\n\t"
;                     "v_fmac_f32_e32 %0, %4, %8\n\t"
;                     "v_fmac_f32_e32 %1, %4, %12\n\t"
;                     "v_fmac_f32_e32 %0, %5, %9\n\t"
;                     "v_fmac_f32_e32 %1, %5, %13\n\t"
;                     "v_fmac_f32_e32 %2, %18, %14\n\t"
;                     "v_add_f32_dpp %0, %0, %0 quad_perm:[1,0,3,2] row_mask:0xf bank_mask:0xf\n\t"
;                     "v_fmac_f32_e32 %3, %18, %15\n\t"
;                     "v_fmac_f32_e32 %4, %18, %16\n\t"
;                     "v_add_f32_dpp %0, %0, %0 quad_perm:[2,3,0,1] row_mask:0xf bank_mask:0xf\n\t"
;                     "v_fmac_f32_e32 %5, %18, %17\n\t"
;                     "s_nop 0\n\t"
;                     "v_add_f32_dpp %0, %0, %0 row_half_mirror row_mask:0xf bank_mask:0xf\n\t"
;                     : "=&v"(sa), "=&v"(yy), "+v"(S0), "+v"(S1), "+v"(S2), "+v"(S3)
;                     : "v"(a.x), "v"(a.y), "v"(a.z), "v"(a.w), "v"(pr.x), "v"(pr.y), "v"(pr.z), "v"(pr.w), "v"(k.x), "v"(k.y), "v"(k.z), "v"(k.w), "v"(v));
;                 if (tl > 0) yb[(tl - 1) * SC_YS + lane] = yy;
;                 const f32x4 b_now = bb; pr = r;
;                 a = a1; bb = bb1; k = k1; r = r1; v = v1;
;                 if (tl + 2 < SC_TC) { const LAS float* sn = st + (tl + 2) * SC_STEP_F;
;                     a1 = *(const LAS f32x4*)(sn); bb1 = *(const LAS f32x4*)(sn + 64); k1 = *(const LAS f32x4*)(sn + 128); r1 = *(const LAS f32x4*)(sn + 192); v1 = vp[(tl + 2) * 32]; }
;                 __builtin_amdgcn_sched_barrier(0);
;                 if (tl + 2 >= SC_TC) asm volatile("s_nop 1");
;                 asm volatile(
;                     "v_add_f32_dpp %4, %4, %4 row_mirror row_mask:0xf bank_mask:0xf\n\t"
;                     "v_fmac_f32_e32 %0, %4, %5\n\t"
;                     "v_fmac_f32_e32 %1, %4, %6\n\t"
;                     "v_fmac_f32_e32 %2, %4, %7\n\t"
;                     "v_fmac_f32_e32 %3, %4, %8\n\t"
	v_add_f32_dpp v192, v192, v192 quad_perm:[1,0,3,2] row_mask:0xf bank_mask:0xf
	v_add_f32_dpp v194, v194, v194 quad_perm:[1,0,3,2] row_mask:0xf bank_mask:0xf
	v_pk_fma_f32 v[122:123], v[148:149], v[140:141], v[122:123] op_sel_hi:[0,1,1]
	v_pk_fma_f32 v[126:127], v[148:149], v[140:141], v[126:127] op_sel:[1,0,0] op_sel_hi:[1,1,1]
	v_add_f32_dpp v192, v192, v192 quad_perm:[2,3,0,1] row_mask:0xf bank_mask:0xf
	v_add_f32_dpp v194, v194, v194 quad_perm:[2,3,0,1] row_mask:0xf bank_mask:0xf
	v_pk_fma_f32 v[124:125], v[148:149], v[142:143], v[124:125] op_sel_hi:[0,1,1]
	v_add_f32_dpp v192, v192, v192 row_half_mirror row_mask:0xf bank_mask:0xf
	v_add_f32_dpp v194, v194, v194 row_half_mirror row_mask:0xf bank_mask:0xf
	v_pk_fma_f32 v[128:129], v[148:149], v[142:143], v[128:129] op_sel:[1,0,0] op_sel_hi:[1,1,1]
	ds_write_b32 v204, v196 offset:2992
	ds_write_b32 v204, v198 offset:11696
	ds_read_b128 v[172:175], v30 offset:14336
	ds_read_b128 v[176:179], v30 offset:14592
	ds_read_b128 v[180:183], v30 offset:14848
	ds_read_b128 v[184:187], v30 offset:15104
	ds_read_b32 v188, v31 offset:1792
	ds_read_b32 v189, v31 offset:1808
	v_add_f32_dpp v192, v192, v192 row_mirror row_mask:0xf bank_mask:0xf
	v_add_f32_dpp v194, v194, v194 row_mirror row_mask:0xf bank_mask:0xf
	v_pk_fma_f32 v[122:123], v[192:193], v[136:137], v[122:123] op_sel_hi:[0,1,1]
	v_pk_fma_f32 v[126:127], v[194:195], v[136:137], v[126:127] op_sel_hi:[0,1,1]
	v_pk_fma_f32 v[124:125], v[192:193], v[138:139], v[124:125] op_sel_hi:[0,1,1]
	v_pk_fma_f32 v[128:129], v[194:195], v[138:139], v[128:129] op_sel_hi:[0,1,1]
	s_waitcnt lgkmcnt(13)
	v_pk_mul_f32 v[192:193], v[122:123], v[152:153]
	v_pk_mul_f32 v[194:195], v[126:127], v[152:153]
	v_pk_mul_f32 v[196:197], v[122:123], v[144:145]
	v_pk_mul_f32 v[198:199], v[126:127], v[144:145]
	v_pk_fma_f32 v[192:193], v[124:125], v[154:155], v[192:193]
	v_pk_fma_f32 v[194:195], v[128:129], v[154:155], v[194:195]
	v_pk_fma_f32 v[196:197], v[124:125], v[146:147], v[196:197]
	v_pk_fma_f32 v[198:199], v[128:129], v[146:147], v[198:199]
	v_add_f32_e32 v192, v192, v193
	v_add_f32_e32 v194, v194, v195
	v_add_f32_e32 v196, v196, v197
	v_add_f32_e32 v198, v198, v199
	s_waitcnt lgkmcnt(8)
	v_add_f32_dpp v192, v192, v192 quad_perm:[1,0,3,2] row_mask:0xf bank_mask:0xf
	v_add_f32_dpp v194, v194, v194 quad_perm:[1,0,3,2] row_mask:0xf bank_mask:0xf
	v_pk_fma_f32 v[122:123], v[168:169], v[160:161], v[122:123] op_sel_hi:[0,1,1]
	v_pk_fma_f32 v[126:127], v[168:169], v[160:161], v[126:127] op_sel:[1,0,0] op_sel_hi:[1,1,1]
	v_add_f32_dpp v192, v192, v192 quad_perm:[2,3,0,1] row_mask:0xf bank_mask:0xf
	v_add_f32_dpp v194, v194, v194 quad_perm:[2,3,0,1] row_mask:0xf bank_mask:0xf
	v_pk_fma_f32 v[124:125], v[168:169], v[162:163], v[124:125] op_sel_hi:[0,1,1]
	v_add_f32_dpp v192, v192, v192 row_half_mirror row_mask:0xf bank_mask:0xf
	v_add_f32_dpp v194, v194, v194 row_half_mirror row_mask:0xf bank_mask:0xf
	v_pk_fma_f32 v[128:129], v[168:169], v[162:163], v[128:129] op_sel:[1,0,0] op_sel_hi:[1,1,1]
	ds_write_b32 v204, v196 offset:3264
	ds_write_b32 v204, v198 offset:11968
	ds_read_b128 v[132:135], v30 offset:15360
	ds_read_b128 v[136:139], v30 offset:15616
	ds_read_b128 v[140:143], v30 offset:15872
	ds_read_b128 v[144:147], v30 offset:16128
	ds_read_b32 v148, v31 offset:1920
	ds_read_b32 v149, v31 offset:1936
	v_add_f32_dpp v192, v192, v192 row_mirror row_mask:0xf bank_mask:0xf
	v_add_f32_dpp v194, v194, v194 row_mirror row_mask:0xf bank_mask:0xf
	v_pk_fma_f32 v[122:123], v[192:193], v[156:157], v[122:123] op_sel_hi:[0,1,1]
	v_pk_fma_f32 v[126:127], v[194:195], v[156:157], v[126:127] op_sel_hi:[0,1,1]
	v_pk_fma_f32 v[124:125], v[192:193], v[158:159], v[124:125] op_sel_hi:[0,1,1]
	v_pk_fma_f32 v[128:129], v[194:195], v[158:159], v[128:129] op_sel_hi:[0,1,1]
	s_waitcnt lgkmcnt(13)
	v_pk_mul_f32 v[192:193], v[122:123], v[172:173]
	v_pk_mul_f32 v[194:195], v[126:127], v[172:173]
	v_pk_mul_f32 v[196:197], v[122:123], v[164:165]
	v_pk_mul_f32 v[198:199], v[126:127], v[164:165]
	v_pk_fma_f32 v[192:193], v[124:125], v[174:175], v[192:193]
	v_pk_fma_f32 v[194:195], v[128:129], v[174:175], v[194:195]
	v_pk_fma_f32 v[196:197], v[124:125], v[166:167], v[196:197]
	v_pk_fma_f32 v[198:199], v[128:129], v[166:167], v[198:199]
	v_add_f32_e32 v192, v192, v193
	v_add_f32_e32 v194, v194, v195
	v_add_f32_e32 v196, v196, v197
	v_add_f32_e32 v198, v198, v199
	s_waitcnt lgkmcnt(8)
	v_add_f32_dpp v192, v192, v192 quad_perm:[1,0,3,2] row_mask:0xf bank_mask:0xf
	v_add_f32_dpp v194, v194, v194 quad_perm:[1,0,3,2] row_mask:0xf bank_mask:0xf
	v_pk_fma_f32 v[122:123], v[188:189], v[180:181], v[122:123] op_sel_hi:[0,1,1]
	v_pk_fma_f32 v[126:127], v[188:189], v[180:181], v[126:127] op_sel:[1,0,0] op_sel_hi:[1,1,1]
	v_add_f32_dpp v192, v192, v192 quad_perm:[2,3,0,1] row_mask:0xf bank_mask:0xf
	v_add_f32_dpp v194, v194, v194 quad_perm:[2,3,0,1] row_mask:0xf bank_mask:0xf
	v_pk_fma_f32 v[124:125], v[188:189], v[182:183], v[124:125] op_sel_hi:[0,1,1]
	v_add_f32_dpp v192, v192, v192 row_half_mirror row_mask:0xf bank_mask:0xf
	v_add_f32_dpp v194, v194, v194 row_half_mirror row_mask:0xf bank_mask:0xf
	v_pk_fma_f32 v[128:129], v[188:189], v[182:183], v[128:129] op_sel:[1,0,0] op_sel_hi:[1,1,1]
	ds_write_b32 v204, v196 offset:3536
	ds_write_b32 v204, v198 offset:12240
	ds_read_b128 v[152:155], v30 offset:16384
	ds_read_b128 v[156:159], v30 offset:16640
	ds_read_b128 v[160:163], v30 offset:16896
	ds_read_b128 v[164:167], v30 offset:17152
	ds_read_b32 v168, v31 offset:2048
	ds_read_b32 v169, v31 offset:2064
	v_add_f32_dpp v192, v192, v192 row_mirror row_mask:0xf bank_mask:0xf
	v_add_f32_dpp v194, v194, v194 row_mirror row_mask:0xf bank_mask:0xf
	v_pk_fma_f32 v[122:123], v[192:193], v[176:177], v[122:123] op_sel_hi:[0,1,1]
	v_pk_fma_f32 v[126:127], v[194:195], v[176:177], v[126:127] op_sel_hi:[0,1,1]
	v_pk_fma_f32 v[124:125], v[192:193], v[178:179], v[124:125] op_sel_hi:[0,1,1]
	v_pk_fma_f32 v[128:129], v[194:195], v[178:179], v[128:129] op_sel_hi:[0,1,1]
	s_waitcnt lgkmcnt(13)
; __device__ __forceinline__ void scan_unit(const Args& A, LAS unsigned char* lds, int s, int tid) {
;     ...
;             for (int tl = 0; tl < SC_TC; ++tl) {
;                 float sa, yy;
;                 asm volatile(
;                     "v_mul_f32_e32 %0, %2, %6\n\t"
;                     "v_mul_f32_e32 %1, %2, %10\n\t"
;                     "v_fmac_f32_e32 %0, %3, %7\n\t"
;                     "v_fmac_f32_e32 %1, %3, %11\n\t"
;                     "v_fmac_f32_e32 %0, %4, %8\n\t"
;                     "v_fmac_f32_e32 %1, %4, %12\n\t"
;                     "v_fmac_f32_e32 %0, %5, %9\n\t"
;                     "v_fmac_f32_e32 %1, %5, %13\n\t"
;                     "v_fmac_f32_e32 %2, %18, %14\n\t"
;                     "v_add_f32_dpp %0, %0, %0 quad_perm:[1,0,3,2] row_mask:0xf bank_mask:0xf\n\t"
;                     "v_fmac_f32_e32 %3, %18, %15\n\t"
;                     "v_fmac_f32_e32 %4, %18, %16\n\t"
;                     "v_add_f32_dpp %0, %0, %0 quad_perm:[2,3,0,1] row_mask:0xf bank_mask:0xf\n\t"
;                     "v_fmac_f32_e32 %5, %18, %17\n\t"
;                     "s_nop 0\n\t"
;                     "v_add_f32_dpp %0, %0, %0 row_half_mirror row_mask:0xf bank_mask:0xf\n\t"
;                     : "=&v"(sa), "=&v"(yy), "+v"(S0), "+v"(S1), "+v"(S2), "+v"(S3)
;                     : "v"(a.x), "v"(a.y), "v"(a.z), "v"(a.w), "v"(pr.x), "v"(pr.y), "v"(pr.z), "v"(pr.w), "v"(k.x), "v"(k.y), "v"(k.z), "v"(k.w), "v"(v));
;                 if (tl > 0) yb[(tl - 1) * SC_YS + lane] = yy;
;                 const f32x4 b_now = bb; pr = r;
;                 a = a1; bb = bb1; k = k1; r = r1; v = v1;
;                 if (tl + 2 < SC_TC) { const LAS float* sn = st + (tl + 2) * SC_STEP_F;
;                     a1 = *(const LAS f32x4*)(sn); bb1 = *(const LAS f32x4*)(sn + 64); k1 = *(const LAS f32x4*)(sn + 128); r1 = *(const LAS f32x4*)(sn + 192); v1 = vp[(tl + 2) * 32]; }
;                 __builtin_amdgcn_sched_barrier(0);
;                 if (tl + 2 >= SC_TC) asm volatile("s_nop 1");
;                 asm volatile(
;                     "v_add_f32_dpp %4, %4, %4 row_mirror row_mask:0xf bank_mask:0xf\n\t"
;                     "v_fmac_f32_e32 %0, %4, %5\n\t"
;                     "v_fmac_f32_e32 %1, %4, %6\n\t"
;                     "v_fmac_f32_e32 %2, %4, %7\n\t"
;                     "v_fmac_f32_e32 %3, %4, %8\n\t"
	v_pk_mul_f32 v[192:193], v[122:123], v[132:133]
	v_pk_mul_f32 v[194:195], v[126:127], v[132:133]
	v_pk_mul_f32 v[196:197], v[122:123], v[184:185]
	v_pk_mul_f32 v[198:199], v[126:127], v[184:185]
	v_pk_fma_f32 v[192:193], v[124:125], v[134:135], v[192:193]
	v_pk_fma_f32 v[194:195], v[128:129], v[134:135], v[194:195]
	v_pk_fma_f32 v[196:197], v[124:125], v[186:187], v[196:197]
	v_pk_fma_f32 v[198:199], v[128:129], v[186:187], v[198:199]
	v_add_f32_e32 v192, v192, v193
	v_add_f32_e32 v194, v194, v195
	v_add_f32_e32 v196, v196, v197
	v_add_f32_e32 v198, v198, v199
	s_waitcnt lgkmcnt(8)
	v_add_f32_dpp v192, v192, v192 quad_perm:[1,0,3,2] row_mask:0xf bank_mask:0xf
	v_add_f32_dpp v194, v194, v194 quad_perm:[1,0,3,2] row_mask:0xf bank_mask:0xf
	v_pk_fma_f32 v[122:123], v[148:149], v[140:141], v[122:123] op_sel_hi:[0,1,1]
	v_pk_fma_f32 v[126:127], v[148:149], v[140:141], v[126:127] op_sel:[1,0,0] op_sel_hi:[1,1,1]
	v_add_f32_dpp v192, v192, v192 quad_perm:[2,3,0,1] row_mask:0xf bank_mask:0xf
	v_add_f32_dpp v194, v194, v194 quad_perm:[2,3,0,1] row_mask:0xf bank_mask:0xf
	v_pk_fma_f32 v[124:125], v[148:149], v[142:143], v[124:125] op_sel_hi:[0,1,1]
	v_add_f32_dpp v192, v192, v192 row_half_mirror row_mask:0xf bank_mask:0xf
	v_add_f32_dpp v194, v194, v194 row_half_mirror row_mask:0xf bank_mask:0xf
	v_pk_fma_f32 v[128:129], v[148:149], v[142:143], v[128:129] op_sel:[1,0,0] op_sel_hi:[1,1,1]
	ds_write_b32 v204, v196 offset:3808
	ds_write_b32 v204, v198 offset:12512
	ds_read_b128 v[172:175], v30 offset:17408
	ds_read_b128 v[176:179], v30 offset:17664
	ds_read_b128 v[180:183], v30 offset:17920
	ds_read_b128 v[184:187], v30 offset:18176
	ds_read_b32 v188, v31 offset:2176
	ds_read_b32 v189, v31 offset:2192
	v_add_f32_dpp v192, v192, v192 row_mirror row_mask:0xf bank_mask:0xf
	v_add_f32_dpp v194, v194, v194 row_mirror row_mask:0xf bank_mask:0xf
	v_pk_fma_f32 v[122:123], v[192:193], v[136:137], v[122:123] op_sel_hi:[0,1,1]
	v_pk_fma_f32 v[126:127], v[194:195], v[136:137], v[126:127] op_sel_hi:[0,1,1]
	v_pk_fma_f32 v[124:125], v[192:193], v[138:139], v[124:125] op_sel_hi:[0,1,1]
	v_pk_fma_f32 v[128:129], v[194:195], v[138:139], v[128:129] op_sel_hi:[0,1,1]
	s_waitcnt lgkmcnt(13)
	v_pk_mul_f32 v[192:193], v[122:123], v[152:153]
	v_pk_mul_f32 v[194:195], v[126:127], v[152:153]
	v_pk_mul_f32 v[196:197], v[122:123], v[144:145]
	v_pk_mul_f32 v[198:199], v[126:127], v[144:145]
	v_pk_fma_f32 v[192:193], v[124:125], v[154:155], v[192:193]
	v_pk_fma_f32 v[194:195], v[128:129], v[154:155], v[194:195]
	v_pk_fma_f32 v[196:197], v[124:125], v[146:147], v[196:197]
	v_pk_fma_f32 v[198:199], v[128:129], v[146:147], v[198:199]
	v_add_f32_e32 v192, v192, v193
	v_add_f32_e32 v194, v194, v195
	v_add_f32_e32 v196, v196, v197
	v_add_f32_e32 v198, v198, v199
	s_waitcnt lgkmcnt(8)
	v_add_f32_dpp v192, v192, v192 quad_perm:[1,0,3,2] row_mask:0xf bank_mask:0xf
	v_add_f32_dpp v194, v194, v194 quad_perm:[1,0,3,2] row_mask:0xf bank_mask:0xf
	v_pk_fma_f32 v[122:123], v[168:169], v[160:161], v[122:123] op_sel_hi:[0,1,1]
	v_pk_fma_f32 v[126:127], v[168:169], v[160:161], v[126:127] op_sel:[1,0,0] op_sel_hi:[1,1,1]
	v_add_f32_dpp v192, v192, v192 quad_perm:[2,3,0,1] row_mask:0xf bank_mask:0xf
	v_add_f32_dpp v194, v194, v194 quad_perm:[2,3,0,1] row_mask:0xf bank_mask:0xf
	v_pk_fma_f32 v[124:125], v[168:169], v[162:163], v[124:125] op_sel_hi:[0,1,1]
	v_add_f32_dpp v192, v192, v192 row_half_mirror row_mask:0xf bank_mask:0xf
	v_add_f32_dpp v194, v194, v194 row_half_mirror row_mask:0xf bank_mask:0xf
	v_pk_fma_f32 v[128:129], v[168:169], v[162:163], v[128:129] op_sel:[1,0,0] op_sel_hi:[1,1,1]
	ds_write_b32 v204, v196 offset:4080
	ds_write_b32 v204, v198 offset:12784
	ds_read_b128 v[132:135], v30 offset:18432
	ds_read_b128 v[136:139], v30 offset:18688
	ds_read_b128 v[140:143], v30 offset:18944
	ds_read_b128 v[144:147], v30 offset:19200
	ds_read_b32 v148, v31 offset:2304
	ds_read_b32 v149, v31 offset:2320
	v_add_f32_dpp v192, v192, v192 row_mirror row_mask:0xf bank_mask:0xf
	v_add_f32_dpp v194, v194, v194 row_mirror row_mask:0xf bank_mask:0xf
	v_pk_fma_f32 v[122:123], v[192:193], v[156:157], v[122:123] op_sel_hi:[0,1,1]
	v_pk_fma_f32 v[126:127], v[194:195], v[156:157], v[126:127] op_sel_hi:[0,1,1]
	v_pk_fma_f32 v[124:125], v[192:193], v[158:159], v[124:125] op_sel_hi:[0,1,1]
	v_pk_fma_f32 v[128:129], v[194:195], v[158:159], v[128:129] op_sel_hi:[0,1,1]
	s_waitcnt lgkmcnt(13)
	v_pk_mul_f32 v[192:193], v[122:123], v[172:173]
	v_pk_mul_f32 v[194:195], v[126:127], v[172:173]
	v_pk_mul_f32 v[196:197], v[122:123], v[164:165]
	v_pk_mul_f32 v[198:199], v[126:127], v[164:165]
	v_pk_fma_f32 v[192:193], v[124:125], v[174:175], v[192:193]
	v_pk_fma_f32 v[194:195], v[128:129], v[174:175], v[194:195]
	v_pk_fma_f32 v[196:197], v[124:125], v[166:167], v[196:197]
	v_pk_fma_f32 v[198:199], v[128:129], v[166:167], v[198:199]
	v_add_f32_e32 v192, v192, v193
	v_add_f32_e32 v194, v194, v195
	v_add_f32_e32 v196, v196, v197
	v_add_f32_e32 v198, v198, v199
	s_waitcnt lgkmcnt(8)
; __device__ __forceinline__ void scan_unit(const Args& A, LAS unsigned char* lds, int s, int tid) {
;     ...
;             for (int tl = 0; tl < SC_TC; ++tl) {
;                 float sa, yy;
;                 asm volatile(
;                     "v_mul_f32_e32 %0, %2, %6\n\t"
;                     "v_mul_f32_e32 %1, %2, %10\n\t"
;                     "v_fmac_f32_e32 %0, %3, %7\n\t"
;                     "v_fmac_f32_e32 %1, %3, %11\n\t"
;                     "v_fmac_f32_e32 %0, %4, %8\n\t"
;                     "v_fmac_f32_e32 %1, %4, %12\n\t"
;                     "v_fmac_f32_e32 %0, %5, %9\n\t"
;                     "v_fmac_f32_e32 %1, %5, %13\n\t"
;                     "v_fmac_f32_e32 %2, %18, %14\n\t"
;                     "v_add_f32_dpp %0, %0, %0 quad_perm:[1,0,3,2] row_mask:0xf bank_mask:0xf\n\t"
;                     "v_fmac_f32_e32 %3, %18, %15\n\t"
;                     "v_fmac_f32_e32 %4, %18, %16\n\t"
;                     "v_add_f32_dpp %0, %0, %0 quad_perm:[2,3,0,1] row_mask:0xf bank_mask:0xf\n\t"
;                     "v_fmac_f32_e32 %5, %18, %17\n\t"
;                     "s_nop 0\n\t"
;                     "v_add_f32_dpp %0, %0, %0 row_half_mirror row_mask:0xf bank_mask:0xf\n\t"
;                     : "=&v"(sa), "=&v"(yy), "+v"(S0), "+v"(S1), "+v"(S2), "+v"(S3)
;                     : "v"(a.x), "v"(a.y), "v"(a.z), "v"(a.w), "v"(pr.x), "v"(pr.y), "v"(pr.z), "v"(pr.w), "v"(k.x), "v"(k.y), "v"(k.z), "v"(k.w), "v"(v));
;                 if (tl > 0) yb[(tl - 1) * SC_YS + lane] = yy;
;                 const f32x4 b_now = bb; pr = r;
;                 a = a1; bb = bb1; k = k1; r = r1; v = v1;
;                 if (tl + 2 < SC_TC) { const LAS float* sn = st + (tl + 2) * SC_STEP_F;
;                     a1 = *(const LAS f32x4*)(sn); bb1 = *(const LAS f32x4*)(sn + 64); k1 = *(const LAS f32x4*)(sn + 128); r1 = *(const LAS f32x4*)(sn + 192); v1 = vp[(tl + 2) * 32]; }
;                 __builtin_amdgcn_sched_barrier(0);
;                 if (tl + 2 >= SC_TC) asm volatile("s_nop 1");
;                 asm volatile(
;                     "v_add_f32_dpp %4, %4, %4 row_mirror row_mask:0xf bank_mask:0xf\n\t"
;                     "v_fmac_f32_e32 %0, %4, %5\n\t"
;                     "v_fmac_f32_e32 %1, %4, %6\n\t"
;                     "v_fmac_f32_e32 %2, %4, %7\n\t"
;                     "v_fmac_f32_e32 %3, %4, %8\n\t"
	v_add_f32_dpp v192, v192, v192 quad_perm:[1,0,3,2] row_mask:0xf bank_mask:0xf
	v_add_f32_dpp v194, v194, v194 quad_perm:[1,0,3,2] row_mask:0xf bank_mask:0xf
	v_pk_fma_f32 v[122:123], v[188:189], v[180:181], v[122:123] op_sel_hi:[0,1,1]
	v_pk_fma_f32 v[126:127], v[188:189], v[180:181], v[126:127] op_sel:[1,0,0] op_sel_hi:[1,1,1]
	v_add_f32_dpp v192, v192, v192 quad_perm:[2,3,0,1] row_mask:0xf bank_mask:0xf
	v_add_f32_dpp v194, v194, v194 quad_perm:[2,3,0,1] row_mask:0xf bank_mask:0xf
	v_pk_fma_f32 v[124:125], v[188:189], v[182:183], v[124:125] op_sel_hi:[0,1,1]
	v_add_f32_dpp v192, v192, v192 row_half_mirror row_mask:0xf bank_mask:0xf
	v_add_f32_dpp v194, v194, v194 row_half_mirror row_mask:0xf bank_mask:0xf
	v_pk_fma_f32 v[128:129], v[188:189], v[182:183], v[128:129] op_sel:[1,0,0] op_sel_hi:[1,1,1]
	ds_write_b32 v204, v196 offset:4352
	ds_write_b32 v204, v198 offset:13056
	ds_read_b128 v[152:155], v30 offset:19456
	ds_read_b128 v[156:159], v30 offset:19712
	ds_read_b128 v[160:163], v30 offset:19968
	ds_read_b128 v[164:167], v30 offset:20224
	ds_read_b32 v168, v31 offset:2432
	ds_read_b32 v169, v31 offset:2448
	v_add_f32_dpp v192, v192, v192 row_mirror row_mask:0xf bank_mask:0xf
	v_add_f32_dpp v194, v194, v194 row_mirror row_mask:0xf bank_mask:0xf
	v_pk_fma_f32 v[122:123], v[192:193], v[176:177], v[122:123] op_sel_hi:[0,1,1]
	v_pk_fma_f32 v[126:127], v[194:195], v[176:177], v[126:127] op_sel_hi:[0,1,1]
	v_pk_fma_f32 v[124:125], v[192:193], v[178:179], v[124:125] op_sel_hi:[0,1,1]
	v_pk_fma_f32 v[128:129], v[194:195], v[178:179], v[128:129] op_sel_hi:[0,1,1]
	s_waitcnt lgkmcnt(13)
	v_pk_mul_f32 v[192:193], v[122:123], v[132:133]
	v_pk_mul_f32 v[194:195], v[126:127], v[132:133]
	v_pk_mul_f32 v[196:197], v[122:123], v[184:185]
	v_pk_mul_f32 v[198:199], v[126:127], v[184:185]
	v_pk_fma_f32 v[192:193], v[124:125], v[134:135], v[192:193]
	v_pk_fma_f32 v[194:195], v[128:129], v[134:135], v[194:195]
	v_pk_fma_f32 v[196:197], v[124:125], v[186:187], v[196:197]
	v_pk_fma_f32 v[198:199], v[128:129], v[186:187], v[198:199]
	v_add_f32_e32 v192, v192, v193
	v_add_f32_e32 v194, v194, v195
	v_add_f32_e32 v196, v196, v197
	v_add_f32_e32 v198, v198, v199
	s_waitcnt lgkmcnt(8)
	v_add_f32_dpp v192, v192, v192 quad_perm:[1,0,3,2] row_mask:0xf bank_mask:0xf
	v_add_f32_dpp v194, v194, v194 quad_perm:[1,0,3,2] row_mask:0xf bank_mask:0xf
	v_pk_fma_f32 v[122:123], v[148:149], v[140:141], v[122:123] op_sel_hi:[0,1,1]
	v_pk_fma_f32 v[126:127], v[148:149], v[140:141], v[126:127] op_sel:[1,0,0] op_sel_hi:[1,1,1]
	v_add_f32_dpp v192, v192, v192 quad_perm:[2,3,0,1] row_mask:0xf bank_mask:0xf
	v_add_f32_dpp v194, v194, v194 quad_perm:[2,3,0,1] row_mask:0xf bank_mask:0xf
	v_pk_fma_f32 v[124:125], v[148:149], v[142:143], v[124:125] op_sel_hi:[0,1,1]
	v_add_f32_dpp v192, v192, v192 row_half_mirror row_mask:0xf bank_mask:0xf
	v_add_f32_dpp v194, v194, v194 row_half_mirror row_mask:0xf bank_mask:0xf
	v_pk_fma_f32 v[128:129], v[148:149], v[142:143], v[128:129] op_sel:[1,0,0] op_sel_hi:[1,1,1]
	ds_write_b32 v204, v196 offset:4624
	ds_write_b32 v204, v198 offset:13328
	ds_read_b128 v[172:175], v30 offset:20480
	ds_read_b128 v[176:179], v30 offset:20736
	ds_read_b128 v[180:183], v30 offset:20992
	ds_read_b128 v[184:187], v30 offset:21248
	ds_read_b32 v188, v31 offset:2560
	ds_read_b32 v189, v31 offset:2576
	v_add_f32_dpp v192, v192, v192 row_mirror row_mask:0xf bank_mask:0xf
	v_add_f32_dpp v194, v194, v194 row_mirror row_mask:0xf bank_mask:0xf
	v_pk_fma_f32 v[122:123], v[192:193], v[136:137], v[122:123] op_sel_hi:[0,1,1]
	v_pk_fma_f32 v[126:127], v[194:195], v[136:137], v[126:127] op_sel_hi:[0,1,1]
	v_pk_fma_f32 v[124:125], v[192:193], v[138:139], v[124:125] op_sel_hi:[0,1,1]
	v_pk_fma_f32 v[128:129], v[194:195], v[138:139], v[128:129] op_sel_hi:[0,1,1]
	s_waitcnt lgkmcnt(13)
	v_pk_mul_f32 v[192:193], v[122:123], v[152:153]
	v_pk_mul_f32 v[194:195], v[126:127], v[152:153]
	v_pk_mul_f32 v[196:197], v[122:123], v[144:145]
	v_pk_mul_f32 v[198:199], v[126:127], v[144:145]
	v_pk_fma_f32 v[192:193], v[124:125], v[154:155], v[192:193]
	v_pk_fma_f32 v[194:195], v[128:129], v[154:155], v[194:195]
	v_pk_fma_f32 v[196:197], v[124:125], v[146:147], v[196:197]
	v_pk_fma_f32 v[198:199], v[128:129], v[146:147], v[198:199]
	v_add_f32_e32 v192, v192, v193
	v_add_f32_e32 v194, v194, v195
	v_add_f32_e32 v196, v196, v197
	v_add_f32_e32 v198, v198, v199
	s_waitcnt lgkmcnt(8)
	v_add_f32_dpp v192, v192, v192 quad_perm:[1,0,3,2] row_mask:0xf bank_mask:0xf
	v_add_f32_dpp v194, v194, v194 quad_perm:[1,0,3,2] row_mask:0xf bank_mask:0xf
	v_pk_fma_f32 v[122:123], v[168:169], v[160:161], v[122:123] op_sel_hi:[0,1,1]
	v_pk_fma_f32 v[126:127], v[168:169], v[160:161], v[126:127] op_sel:[1,0,0] op_sel_hi:[1,1,1]
	v_add_f32_dpp v192, v192, v192 quad_perm:[2,3,0,1] row_mask:0xf bank_mask:0xf
	v_add_f32_dpp v194, v194, v194 quad_perm:[2,3,0,1] row_mask:0xf bank_mask:0xf
	v_pk_fma_f32 v[124:125], v[168:169], v[162:163], v[124:125] op_sel_hi:[0,1,1]
	v_add_f32_dpp v192, v192, v192 row_half_mirror row_mask:0xf bank_mask:0xf
	v_add_f32_dpp v194, v194, v194 row_half_mirror row_mask:0xf bank_mask:0xf
	v_pk_fma_f32 v[128:129], v[168:169], v[162:163], v[128:129] op_sel:[1,0,0] op_sel_hi:[1,1,1]
	ds_write_b32 v204, v196 offset:4896
	ds_write_b32 v204, v198 offset:13600
	ds_read_b128 v[132:135], v30 offset:21504
	ds_read_b128 v[136:139], v30 offset:21760
	ds_read_b128 v[140:143], v30 offset:22016
	ds_read_b128 v[144:147], v30 offset:22272
	ds_read_b32 v148, v31 offset:2688
	ds_read_b32 v149, v31 offset:2704
	v_add_f32_dpp v192, v192, v192 row_mirror row_mask:0xf bank_mask:0xf
	v_add_f32_dpp v194, v194, v194 row_mirror row_mask:0xf bank_mask:0xf
	v_pk_fma_f32 v[122:123], v[192:193], v[156:157], v[122:123] op_sel_hi:[0,1,1]
	v_pk_fma_f32 v[126:127], v[194:195], v[156:157], v[126:127] op_sel_hi:[0,1,1]
	v_pk_fma_f32 v[124:125], v[192:193], v[158:159], v[124:125] op_sel_hi:[0,1,1]
	v_pk_fma_f32 v[128:129], v[194:195], v[158:159], v[128:129] op_sel_hi:[0,1,1]
	s_waitcnt lgkmcnt(13)
; __device__ __forceinline__ void scan_unit(const Args& A, LAS unsigned char* lds, int s, int tid) {
;     ...
;             for (int tl = 0; tl < SC_TC; ++tl) {
;                 float sa, yy;
;                 asm volatile(
;                     "v_mul_f32_e32 %0, %2, %6\n\t"
;                     "v_mul_f32_e32 %1, %2, %10\n\t"
;                     "v_fmac_f32_e32 %0, %3, %7\n\t"
;                     "v_fmac_f32_e32 %1, %3, %11\n\t"
;                     "v_fmac_f32_e32 %0, %4, %8\n\t"
;                     "v_fmac_f32_e32 %1, %4, %12\n\t"
;                     "v_fmac_f32_e32 %0, %5, %9\n\t"
;                     "v_fmac_f32_e32 %1, %5, %13\n\t"
;                     "v_fmac_f32_e32 %2, %18, %14\n\t"
;                     "v_add_f32_dpp %0, %0, %0 quad_perm:[1,0,3,2] row_mask:0xf bank_mask:0xf\n\t"
;                     "v_fmac_f32_e32 %3, %18, %15\n\t"
;                     "v_fmac_f32_e32 %4, %18, %16\n\t"
;                     "v_add_f32_dpp %0, %0, %0 quad_perm:[2,3,0,1] row_mask:0xf bank_mask:0xf\n\t"
;                     "v_fmac_f32_e32 %5, %18, %17\n\t"
;                     "s_nop 0\n\t"
;                     "v_add_f32_dpp %0, %0, %0 row_half_mirror row_mask:0xf bank_mask:0xf\n\t"
;                     : "=&v"(sa), "=&v"(yy), "+v"(S0), "+v"(S1), "+v"(S2), "+v"(S3)
;                     : "v"(a.x), "v"(a.y), "v"(a.z), "v"(a.w), "v"(pr.x), "v"(pr.y), "v"(pr.z), "v"(pr.w), "v"(k.x), "v"(k.y), "v"(k.z), "v"(k.w), "v"(v));
;                 if (tl > 0) yb[(tl - 1) * SC_YS + lane] = yy;
;                 const f32x4 b_now = bb; pr = r;
;                 a = a1; bb = bb1; k = k1; r = r1; v = v1;
;                 if (tl + 2 < SC_TC) { const LAS float* sn = st + (tl + 2) * SC_STEP_F;
;                     a1 = *(const LAS f32x4*)(sn); bb1 = *(const LAS f32x4*)(sn + 64); k1 = *(const LAS f32x4*)(sn + 128); r1 = *(const LAS f32x4*)(sn + 192); v1 = vp[(tl + 2) * 32]; }
;                 __builtin_amdgcn_sched_barrier(0);
;                 if (tl + 2 >= SC_TC) asm volatile("s_nop 1");
;                 asm volatile(
;                     "v_add_f32_dpp %4, %4, %4 row_mirror row_mask:0xf bank_mask:0xf\n\t"
;                     "v_fmac_f32_e32 %0, %4, %5\n\t"
;                     "v_fmac_f32_e32 %1, %4, %6\n\t"
;                     "v_fmac_f32_e32 %2, %4, %7\n\t"
;                     "v_fmac_f32_e32 %3, %4, %8\n\t"
	v_pk_mul_f32 v[192:193], v[122:123], v[172:173]
	v_pk_mul_f32 v[194:195], v[126:127], v[172:173]
	v_pk_mul_f32 v[196:197], v[122:123], v[164:165]
	v_pk_mul_f32 v[198:199], v[126:127], v[164:165]
	v_pk_fma_f32 v[192:193], v[124:125], v[174:175], v[192:193]
	v_pk_fma_f32 v[194:195], v[128:129], v[174:175], v[194:195]
	v_pk_fma_f32 v[196:197], v[124:125], v[166:167], v[196:197]
	v_pk_fma_f32 v[198:199], v[128:129], v[166:167], v[198:199]
	v_add_f32_e32 v192, v192, v193
	v_add_f32_e32 v194, v194, v195
	v_add_f32_e32 v196, v196, v197
	v_add_f32_e32 v198, v198, v199
	s_waitcnt lgkmcnt(8)
	v_add_f32_dpp v192, v192, v192 quad_perm:[1,0,3,2] row_mask:0xf bank_mask:0xf
	v_add_f32_dpp v194, v194, v194 quad_perm:[1,0,3,2] row_mask:0xf bank_mask:0xf
	v_pk_fma_f32 v[122:123], v[188:189], v[180:181], v[122:123] op_sel_hi:[0,1,1]
	v_pk_fma_f32 v[126:127], v[188:189], v[180:181], v[126:127] op_sel:[1,0,0] op_sel_hi:[1,1,1]
	v_add_f32_dpp v192, v192, v192 quad_perm:[2,3,0,1] row_mask:0xf bank_mask:0xf
	v_add_f32_dpp v194, v194, v194 quad_perm:[2,3,0,1] row_mask:0xf bank_mask:0xf
	v_pk_fma_f32 v[124:125], v[188:189], v[182:183], v[124:125] op_sel_hi:[0,1,1]
	v_add_f32_dpp v192, v192, v192 row_half_mirror row_mask:0xf bank_mask:0xf
	v_add_f32_dpp v194, v194, v194 row_half_mirror row_mask:0xf bank_mask:0xf
	v_pk_fma_f32 v[128:129], v[188:189], v[182:183], v[128:129] op_sel:[1,0,0] op_sel_hi:[1,1,1]
	ds_write_b32 v204, v196 offset:5168
	ds_write_b32 v204, v198 offset:13872
	ds_read_b128 v[152:155], v30 offset:22528
	ds_read_b128 v[156:159], v30 offset:22784
	ds_read_b128 v[160:163], v30 offset:23040
	ds_read_b128 v[164:167], v30 offset:23296
	ds_read_b32 v168, v31 offset:2816
	ds_read_b32 v169, v31 offset:2832
	v_add_f32_dpp v192, v192, v192 row_mirror row_mask:0xf bank_mask:0xf
	v_add_f32_dpp v194, v194, v194 row_mirror row_mask:0xf bank_mask:0xf
	v_pk_fma_f32 v[122:123], v[192:193], v[176:177], v[122:123] op_sel_hi:[0,1,1]
	v_pk_fma_f32 v[126:127], v[194:195], v[176:177], v[126:127] op_sel_hi:[0,1,1]
	v_pk_fma_f32 v[124:125], v[192:193], v[178:179], v[124:125] op_sel_hi:[0,1,1]
	v_pk_fma_f32 v[128:129], v[194:195], v[178:179], v[128:129] op_sel_hi:[0,1,1]
	s_waitcnt lgkmcnt(13)
	v_pk_mul_f32 v[192:193], v[122:123], v[132:133]
	v_pk_mul_f32 v[194:195], v[126:127], v[132:133]
	v_pk_mul_f32 v[196:197], v[122:123], v[184:185]
	v_pk_mul_f32 v[198:199], v[126:127], v[184:185]
	v_pk_fma_f32 v[192:193], v[124:125], v[134:135], v[192:193]
	v_pk_fma_f32 v[194:195], v[128:129], v[134:135], v[194:195]
	v_pk_fma_f32 v[196:197], v[124:125], v[186:187], v[196:197]
	v_pk_fma_f32 v[198:199], v[128:129], v[186:187], v[198:199]
	v_add_f32_e32 v192, v192, v193
	v_add_f32_e32 v194, v194, v195
	v_add_f32_e32 v196, v196, v197
	v_add_f32_e32 v198, v198, v199
	s_waitcnt lgkmcnt(8)
	v_add_f32_dpp v192, v192, v192 quad_perm:[1,0,3,2] row_mask:0xf bank_mask:0xf
	v_add_f32_dpp v194, v194, v194 quad_perm:[1,0,3,2] row_mask:0xf bank_mask:0xf
	v_pk_fma_f32 v[122:123], v[148:149], v[140:141], v[122:123] op_sel_hi:[0,1,1]
	v_pk_fma_f32 v[126:127], v[148:149], v[140:141], v[126:127] op_sel:[1,0,0] op_sel_hi:[1,1,1]
	v_add_f32_dpp v192, v192, v192 quad_perm:[2,3,0,1] row_mask:0xf bank_mask:0xf
	v_add_f32_dpp v194, v194, v194 quad_perm:[2,3,0,1] row_mask:0xf bank_mask:0xf
	v_pk_fma_f32 v[124:125], v[148:149], v[142:143], v[124:125] op_sel_hi:[0,1,1]
	v_add_f32_dpp v192, v192, v192 row_half_mirror row_mask:0xf bank_mask:0xf
	v_add_f32_dpp v194, v194, v194 row_half_mirror row_mask:0xf bank_mask:0xf
	v_pk_fma_f32 v[128:129], v[148:149], v[142:143], v[128:129] op_sel:[1,0,0] op_sel_hi:[1,1,1]
	ds_write_b32 v204, v196 offset:5440
	ds_write_b32 v204, v198 offset:14144
	ds_read_b128 v[172:175], v30 offset:23552
	ds_read_b128 v[176:179], v30 offset:23808
	ds_read_b128 v[180:183], v30 offset:24064
	ds_read_b128 v[184:187], v30 offset:24320
	ds_read_b32 v188, v31 offset:2944
	ds_read_b32 v189, v31 offset:2960
	v_add_f32_dpp v192, v192, v192 row_mirror row_mask:0xf bank_mask:0xf
	v_add_f32_dpp v194, v194, v194 row_mirror row_mask:0xf bank_mask:0xf
	v_pk_fma_f32 v[122:123], v[192:193], v[136:137], v[122:123] op_sel_hi:[0,1,1]
	v_pk_fma_f32 v[126:127], v[194:195], v[136:137], v[126:127] op_sel_hi:[0,1,1]
	v_pk_fma_f32 v[124:125], v[192:193], v[138:139], v[124:125] op_sel_hi:[0,1,1]
	v_pk_fma_f32 v[128:129], v[194:195], v[138:139], v[128:129] op_sel_hi:[0,1,1]
	s_waitcnt lgkmcnt(13)
	v_pk_mul_f32 v[192:193], v[122:123], v[152:153]
	v_pk_mul_f32 v[194:195], v[126:127], v[152:153]
	v_pk_mul_f32 v[196:197], v[122:123], v[144:145]
	v_pk_mul_f32 v[198:199], v[126:127], v[144:145]
	v_pk_fma_f32 v[192:193], v[124:125], v[154:155], v[192:193]
	v_pk_fma_f32 v[194:195], v[128:129], v[154:155], v[194:195]
	v_pk_fma_f32 v[196:197], v[124:125], v[146:147], v[196:197]
	v_pk_fma_f32 v[198:199], v[128:129], v[146:147], v[198:199]
	v_add_f32_e32 v192, v192, v193
	v_add_f32_e32 v194, v194, v195
	v_add_f32_e32 v196, v196, v197
	v_add_f32_e32 v198, v198, v199
	s_waitcnt lgkmcnt(8)
; __device__ __forceinline__ void scan_unit(const Args& A, LAS unsigned char* lds, int s, int tid) {
;     ...
;             for (int tl = 0; tl < SC_TC; ++tl) {
;                 float sa, yy;
;                 asm volatile(
;                     "v_mul_f32_e32 %0, %2, %6\n\t"
;                     "v_mul_f32_e32 %1, %2, %10\n\t"
;                     "v_fmac_f32_e32 %0, %3, %7\n\t"
;                     "v_fmac_f32_e32 %1, %3, %11\n\t"
;                     "v_fmac_f32_e32 %0, %4, %8\n\t"
;                     "v_fmac_f32_e32 %1, %4, %12\n\t"
;                     "v_fmac_f32_e32 %0, %5, %9\n\t"
;                     "v_fmac_f32_e32 %1, %5, %13\n\t"
;                     "v_fmac_f32_e32 %2, %18, %14\n\t"
;                     "v_add_f32_dpp %0, %0, %0 quad_perm:[1,0,3,2] row_mask:0xf bank_mask:0xf\n\t"
;                     "v_fmac_f32_e32 %3, %18, %15\n\t"
;                     "v_fmac_f32_e32 %4, %18, %16\n\t"
;                     "v_add_f32_dpp %0, %0, %0 quad_perm:[2,3,0,1] row_mask:0xf bank_mask:0xf\n\t"
;                     "v_fmac_f32_e32 %5, %18, %17\n\t"
;                     "s_nop 0\n\t"
;                     "v_add_f32_dpp %0, %0, %0 row_half_mirror row_mask:0xf bank_mask:0xf\n\t"
;                     : "=&v"(sa), "=&v"(yy), "+v"(S0), "+v"(S1), "+v"(S2), "+v"(S3)
;                     : "v"(a.x), "v"(a.y), "v"(a.z), "v"(a.w), "v"(pr.x), "v"(pr.y), "v"(pr.z), "v"(pr.w), "v"(k.x), "v"(k.y), "v"(k.z), "v"(k.w), "v"(v));
;                 if (tl > 0) yb[(tl - 1) * SC_YS + lane] = yy;
;                 const f32x4 b_now = bb; pr = r;
;                 a = a1; bb = bb1; k = k1; r = r1; v = v1;
;                 if (tl + 2 < SC_TC) { const LAS float* sn = st + (tl + 2) * SC_STEP_F;
;                     a1 = *(const LAS f32x4*)(sn); bb1 = *(const LAS f32x4*)(sn + 64); k1 = *(const LAS f32x4*)(sn + 128); r1 = *(const LAS f32x4*)(sn + 192); v1 = vp[(tl + 2) * 32]; }
;                 __builtin_amdgcn_sched_barrier(0);
;                 if (tl + 2 >= SC_TC) asm volatile("s_nop 1");
;                 asm volatile(
;                     "v_add_f32_dpp %4, %4, %4 row_mirror row_mask:0xf bank_mask:0xf\n\t"
;                     "v_fmac_f32_e32 %0, %4, %5\n\t"
;                     "v_fmac_f32_e32 %1, %4, %6\n\t"
;                     "v_fmac_f32_e32 %2, %4, %7\n\t"
;                     "v_fmac_f32_e32 %3, %4, %8\n\t"
	v_add_f32_dpp v192, v192, v192 quad_perm:[1,0,3,2] row_mask:0xf bank_mask:0xf
	v_add_f32_dpp v194, v194, v194 quad_perm:[1,0,3,2] row_mask:0xf bank_mask:0xf
	v_pk_fma_f32 v[122:123], v[168:169], v[160:161], v[122:123] op_sel_hi:[0,1,1]
	v_pk_fma_f32 v[126:127], v[168:169], v[160:161], v[126:127] op_sel:[1,0,0] op_sel_hi:[1,1,1]
	v_add_f32_dpp v192, v192, v192 quad_perm:[2,3,0,1] row_mask:0xf bank_mask:0xf
	v_add_f32_dpp v194, v194, v194 quad_perm:[2,3,0,1] row_mask:0xf bank_mask:0xf
	v_pk_fma_f32 v[124:125], v[168:169], v[162:163], v[124:125] op_sel_hi:[0,1,1]
	v_add_f32_dpp v192, v192, v192 row_half_mirror row_mask:0xf bank_mask:0xf
	v_add_f32_dpp v194, v194, v194 row_half_mirror row_mask:0xf bank_mask:0xf
	v_pk_fma_f32 v[128:129], v[168:169], v[162:163], v[128:129] op_sel:[1,0,0] op_sel_hi:[1,1,1]
	ds_write_b32 v204, v196 offset:5712
	ds_write_b32 v204, v198 offset:14416
	ds_read_b128 v[132:135], v30 offset:24576
	ds_read_b128 v[136:139], v30 offset:24832
	ds_read_b128 v[140:143], v30 offset:25088
	ds_read_b128 v[144:147], v30 offset:25344
	ds_read_b32 v148, v31 offset:3072
	ds_read_b32 v149, v31 offset:3088
	v_add_f32_dpp v192, v192, v192 row_mirror row_mask:0xf bank_mask:0xf
	v_add_f32_dpp v194, v194, v194 row_mirror row_mask:0xf bank_mask:0xf
	v_pk_fma_f32 v[122:123], v[192:193], v[156:157], v[122:123] op_sel_hi:[0,1,1]
	v_pk_fma_f32 v[126:127], v[194:195], v[156:157], v[126:127] op_sel_hi:[0,1,1]
	v_pk_fma_f32 v[124:125], v[192:193], v[158:159], v[124:125] op_sel_hi:[0,1,1]
	v_pk_fma_f32 v[128:129], v[194:195], v[158:159], v[128:129] op_sel_hi:[0,1,1]
	s_waitcnt lgkmcnt(13)
	v_pk_mul_f32 v[192:193], v[122:123], v[172:173]
	v_pk_mul_f32 v[194:195], v[126:127], v[172:173]
	v_pk_mul_f32 v[196:197], v[122:123], v[164:165]
	v_pk_mul_f32 v[198:199], v[126:127], v[164:165]
	v_pk_fma_f32 v[192:193], v[124:125], v[174:175], v[192:193]
	v_pk_fma_f32 v[194:195], v[128:129], v[174:175], v[194:195]
	v_pk_fma_f32 v[196:197], v[124:125], v[166:167], v[196:197]
	v_pk_fma_f32 v[198:199], v[128:129], v[166:167], v[198:199]
	v_add_f32_e32 v192, v192, v193
	v_add_f32_e32 v194, v194, v195
	v_add_f32_e32 v196, v196, v197
	v_add_f32_e32 v198, v198, v199
	s_waitcnt lgkmcnt(8)
	v_add_f32_dpp v192, v192, v192 quad_perm:[1,0,3,2] row_mask:0xf bank_mask:0xf
	v_add_f32_dpp v194, v194, v194 quad_perm:[1,0,3,2] row_mask:0xf bank_mask:0xf
	v_pk_fma_f32 v[122:123], v[188:189], v[180:181], v[122:123] op_sel_hi:[0,1,1]
	v_pk_fma_f32 v[126:127], v[188:189], v[180:181], v[126:127] op_sel:[1,0,0] op_sel_hi:[1,1,1]
	v_add_f32_dpp v192, v192, v192 quad_perm:[2,3,0,1] row_mask:0xf bank_mask:0xf
	v_add_f32_dpp v194, v194, v194 quad_perm:[2,3,0,1] row_mask:0xf bank_mask:0xf
	v_pk_fma_f32 v[124:125], v[188:189], v[182:183], v[124:125] op_sel_hi:[0,1,1]
	v_add_f32_dpp v192, v192, v192 row_half_mirror row_mask:0xf bank_mask:0xf
	v_add_f32_dpp v194, v194, v194 row_half_mirror row_mask:0xf bank_mask:0xf
	v_pk_fma_f32 v[128:129], v[188:189], v[182:183], v[128:129] op_sel:[1,0,0] op_sel_hi:[1,1,1]
	ds_write_b32 v204, v196 offset:5984
	ds_write_b32 v204, v198 offset:14688
	ds_read_b128 v[152:155], v30 offset:25600
	ds_read_b128 v[156:159], v30 offset:25856
	ds_read_b128 v[160:163], v30 offset:26112
	ds_read_b128 v[164:167], v30 offset:26368
	ds_read_b32 v168, v31 offset:3200
	ds_read_b32 v169, v31 offset:3216
	v_add_f32_dpp v192, v192, v192 row_mirror row_mask:0xf bank_mask:0xf
	v_add_f32_dpp v194, v194, v194 row_mirror row_mask:0xf bank_mask:0xf
	v_pk_fma_f32 v[122:123], v[192:193], v[176:177], v[122:123] op_sel_hi:[0,1,1]
	v_pk_fma_f32 v[126:127], v[194:195], v[176:177], v[126:127] op_sel_hi:[0,1,1]
	v_pk_fma_f32 v[124:125], v[192:193], v[178:179], v[124:125] op_sel_hi:[0,1,1]
	v_pk_fma_f32 v[128:129], v[194:195], v[178:179], v[128:129] op_sel_hi:[0,1,1]
	s_waitcnt lgkmcnt(13)
	v_pk_mul_f32 v[192:193], v[122:123], v[132:133]
	v_pk_mul_f32 v[194:195], v[126:127], v[132:133]
	v_pk_mul_f32 v[196:197], v[122:123], v[184:185]
	v_pk_mul_f32 v[198:199], v[126:127], v[184:185]
	v_pk_fma_f32 v[192:193], v[124:125], v[134:135], v[192:193]
	v_pk_fma_f32 v[194:195], v[128:129], v[134:135], v[194:195]
	v_pk_fma_f32 v[196:197], v[124:125], v[186:187], v[196:197]
	v_pk_fma_f32 v[198:199], v[128:129], v[186:187], v[198:199]
	v_add_f32_e32 v192, v192, v193
	v_add_f32_e32 v194, v194, v195
	v_add_f32_e32 v196, v196, v197
	v_add_f32_e32 v198, v198, v199
	s_waitcnt lgkmcnt(8)
	v_add_f32_dpp v192, v192, v192 quad_perm:[1,0,3,2] row_mask:0xf bank_mask:0xf
	v_add_f32_dpp v194, v194, v194 quad_perm:[1,0,3,2] row_mask:0xf bank_mask:0xf
	v_pk_fma_f32 v[122:123], v[148:149], v[140:141], v[122:123] op_sel_hi:[0,1,1]
	v_pk_fma_f32 v[126:127], v[148:149], v[140:141], v[126:127] op_sel:[1,0,0] op_sel_hi:[1,1,1]
	v_add_f32_dpp v192, v192, v192 quad_perm:[2,3,0,1] row_mask:0xf bank_mask:0xf
	v_add_f32_dpp v194, v194, v194 quad_perm:[2,3,0,1] row_mask:0xf bank_mask:0xf
	v_pk_fma_f32 v[124:125], v[148:149], v[142:143], v[124:125] op_sel_hi:[0,1,1]
	v_add_f32_dpp v192, v192, v192 row_half_mirror row_mask:0xf bank_mask:0xf
	v_add_f32_dpp v194, v194, v194 row_half_mirror row_mask:0xf bank_mask:0xf
	v_pk_fma_f32 v[128:129], v[148:149], v[142:143], v[128:129] op_sel:[1,0,0] op_sel_hi:[1,1,1]
	ds_write_b32 v204, v196 offset:6256
	ds_write_b32 v204, v198 offset:14960
	ds_read_b128 v[172:175], v30 offset:26624
	ds_read_b128 v[176:179], v30 offset:26880
	ds_read_b128 v[180:183], v30 offset:27136
	ds_read_b128 v[184:187], v30 offset:27392
	ds_read_b32 v188, v31 offset:3328
	ds_read_b32 v189, v31 offset:3344
	v_add_f32_dpp v192, v192, v192 row_mirror row_mask:0xf bank_mask:0xf
	v_add_f32_dpp v194, v194, v194 row_mirror row_mask:0xf bank_mask:0xf
	v_pk_fma_f32 v[122:123], v[192:193], v[136:137], v[122:123] op_sel_hi:[0,1,1]
	v_pk_fma_f32 v[126:127], v[194:195], v[136:137], v[126:127] op_sel_hi:[0,1,1]
	v_pk_fma_f32 v[124:125], v[192:193], v[138:139], v[124:125] op_sel_hi:[0,1,1]
	v_pk_fma_f32 v[128:129], v[194:195], v[138:139], v[128:129] op_sel_hi:[0,1,1]
	s_waitcnt lgkmcnt(13)
; __device__ __forceinline__ void scan_unit(const Args& A, LAS unsigned char* lds, int s, int tid) {
;     ...
;             for (int tl = 0; tl < SC_TC; ++tl) {
;                 float sa, yy;
;                 asm volatile(
;                     "v_mul_f32_e32 %0, %2, %6\n\t"
;                     "v_mul_f32_e32 %1, %2, %10\n\t"
;                     "v_fmac_f32_e32 %0, %3, %7\n\t"
;                     "v_fmac_f32_e32 %1, %3, %11\n\t"
;                     "v_fmac_f32_e32 %0, %4, %8\n\t"
;                     "v_fmac_f32_e32 %1, %4, %12\n\t"
;                     "v_fmac_f32_e32 %0, %5, %9\n\t"
;                     "v_fmac_f32_e32 %1, %5, %13\n\t"
;                     "v_fmac_f32_e32 %2, %18, %14\n\t"
;                     "v_add_f32_dpp %0, %0, %0 quad_perm:[1,0,3,2] row_mask:0xf bank_mask:0xf\n\t"
;                     "v_fmac_f32_e32 %3, %18, %15\n\t"
;                     "v_fmac_f32_e32 %4, %18, %16\n\t"
;                     "v_add_f32_dpp %0, %0, %0 quad_perm:[2,3,0,1] row_mask:0xf bank_mask:0xf\n\t"
;                     "v_fmac_f32_e32 %5, %18, %17\n\t"
;                     "s_nop 0\n\t"
;                     "v_add_f32_dpp %0, %0, %0 row_half_mirror row_mask:0xf bank_mask:0xf\n\t"
;                     : "=&v"(sa), "=&v"(yy), "+v"(S0), "+v"(S1), "+v"(S2), "+v"(S3)
;                     : "v"(a.x), "v"(a.y), "v"(a.z), "v"(a.w), "v"(pr.x), "v"(pr.y), "v"(pr.z), "v"(pr.w), "v"(k.x), "v"(k.y), "v"(k.z), "v"(k.w), "v"(v));
;                 if (tl > 0) yb[(tl - 1) * SC_YS + lane] = yy;
;                 const f32x4 b_now = bb; pr = r;
;                 a = a1; bb = bb1; k = k1; r = r1; v = v1;
;                 if (tl + 2 < SC_TC) { const LAS float* sn = st + (tl + 2) * SC_STEP_F;
;                     a1 = *(const LAS f32x4*)(sn); bb1 = *(const LAS f32x4*)(sn + 64); k1 = *(const LAS f32x4*)(sn + 128); r1 = *(const LAS f32x4*)(sn + 192); v1 = vp[(tl + 2) * 32]; }
;                 __builtin_amdgcn_sched_barrier(0);
;                 if (tl + 2 >= SC_TC) asm volatile("s_nop 1");
;                 asm volatile(
;                     "v_add_f32_dpp %4, %4, %4 row_mirror row_mask:0xf bank_mask:0xf\n\t"
;                     "v_fmac_f32_e32 %0, %4, %5\n\t"
;                     "v_fmac_f32_e32 %1, %4, %6\n\t"
;                     "v_fmac_f32_e32 %2, %4, %7\n\t"
;                     "v_fmac_f32_e32 %3, %4, %8\n\t"
	v_pk_mul_f32 v[192:193], v[122:123], v[152:153]
	v_pk_mul_f32 v[194:195], v[126:127], v[152:153]
	v_pk_mul_f32 v[196:197], v[122:123], v[144:145]
	v_pk_mul_f32 v[198:199], v[126:127], v[144:145]
	v_pk_fma_f32 v[192:193], v[124:125], v[154:155], v[192:193]
	v_pk_fma_f32 v[194:195], v[128:129], v[154:155], v[194:195]
	v_pk_fma_f32 v[196:197], v[124:125], v[146:147], v[196:197]
	v_pk_fma_f32 v[198:199], v[128:129], v[146:147], v[198:199]
	v_add_f32_e32 v192, v192, v193
	v_add_f32_e32 v194, v194, v195
	v_add_f32_e32 v196, v196, v197
	v_add_f32_e32 v198, v198, v199
	s_waitcnt lgkmcnt(8)
	v_add_f32_dpp v192, v192, v192 quad_perm:[1,0,3,2] row_mask:0xf bank_mask:0xf
	v_add_f32_dpp v194, v194, v194 quad_perm:[1,0,3,2] row_mask:0xf bank_mask:0xf
	v_pk_fma_f32 v[122:123], v[168:169], v[160:161], v[122:123] op_sel_hi:[0,1,1]
	v_pk_fma_f32 v[126:127], v[168:169], v[160:161], v[126:127] op_sel:[1,0,0] op_sel_hi:[1,1,1]
	v_add_f32_dpp v192, v192, v192 quad_perm:[2,3,0,1] row_mask:0xf bank_mask:0xf
	v_add_f32_dpp v194, v194, v194 quad_perm:[2,3,0,1] row_mask:0xf bank_mask:0xf
	v_pk_fma_f32 v[124:125], v[168:169], v[162:163], v[124:125] op_sel_hi:[0,1,1]
	v_add_f32_dpp v192, v192, v192 row_half_mirror row_mask:0xf bank_mask:0xf
	v_add_f32_dpp v194, v194, v194 row_half_mirror row_mask:0xf bank_mask:0xf
	v_pk_fma_f32 v[128:129], v[168:169], v[162:163], v[128:129] op_sel:[1,0,0] op_sel_hi:[1,1,1]
	ds_write_b32 v204, v196 offset:6528
	ds_write_b32 v204, v198 offset:15232
	ds_read_b128 v[132:135], v30 offset:27648
	ds_read_b128 v[136:139], v30 offset:27904
	ds_read_b128 v[140:143], v30 offset:28160
	ds_read_b128 v[144:147], v30 offset:28416
	ds_read_b32 v148, v31 offset:3456
	ds_read_b32 v149, v31 offset:3472
	v_add_f32_dpp v192, v192, v192 row_mirror row_mask:0xf bank_mask:0xf
	v_add_f32_dpp v194, v194, v194 row_mirror row_mask:0xf bank_mask:0xf
	v_pk_fma_f32 v[122:123], v[192:193], v[156:157], v[122:123] op_sel_hi:[0,1,1]
	v_pk_fma_f32 v[126:127], v[194:195], v[156:157], v[126:127] op_sel_hi:[0,1,1]
	v_pk_fma_f32 v[124:125], v[192:193], v[158:159], v[124:125] op_sel_hi:[0,1,1]
	v_pk_fma_f32 v[128:129], v[194:195], v[158:159], v[128:129] op_sel_hi:[0,1,1]
	s_waitcnt lgkmcnt(13)
	v_pk_mul_f32 v[192:193], v[122:123], v[172:173]
	v_pk_mul_f32 v[194:195], v[126:127], v[172:173]
	v_pk_mul_f32 v[196:197], v[122:123], v[164:165]
	v_pk_mul_f32 v[198:199], v[126:127], v[164:165]
	v_pk_fma_f32 v[192:193], v[124:125], v[174:175], v[192:193]
	v_pk_fma_f32 v[194:195], v[128:129], v[174:175], v[194:195]
	v_pk_fma_f32 v[196:197], v[124:125], v[166:167], v[196:197]
	v_pk_fma_f32 v[198:199], v[128:129], v[166:167], v[198:199]
	v_add_f32_e32 v192, v192, v193
	v_add_f32_e32 v194, v194, v195
	v_add_f32_e32 v196, v196, v197
	v_add_f32_e32 v198, v198, v199
	s_waitcnt lgkmcnt(8)
	v_add_f32_dpp v192, v192, v192 quad_perm:[1,0,3,2] row_mask:0xf bank_mask:0xf
	v_add_f32_dpp v194, v194, v194 quad_perm:[1,0,3,2] row_mask:0xf bank_mask:0xf
	v_pk_fma_f32 v[122:123], v[188:189], v[180:181], v[122:123] op_sel_hi:[0,1,1]
	v_pk_fma_f32 v[126:127], v[188:189], v[180:181], v[126:127] op_sel:[1,0,0] op_sel_hi:[1,1,1]
	v_add_f32_dpp v192, v192, v192 quad_perm:[2,3,0,1] row_mask:0xf bank_mask:0xf
	v_add_f32_dpp v194, v194, v194 quad_perm:[2,3,0,1] row_mask:0xf bank_mask:0xf
	v_pk_fma_f32 v[124:125], v[188:189], v[182:183], v[124:125] op_sel_hi:[0,1,1]
	v_add_f32_dpp v192, v192, v192 row_half_mirror row_mask:0xf bank_mask:0xf
	v_add_f32_dpp v194, v194, v194 row_half_mirror row_mask:0xf bank_mask:0xf
	v_pk_fma_f32 v[128:129], v[188:189], v[182:183], v[128:129] op_sel:[1,0,0] op_sel_hi:[1,1,1]
	ds_write_b32 v204, v196 offset:6800
	ds_write_b32 v204, v198 offset:15504
	ds_read_b128 v[152:155], v30 offset:28672
	ds_read_b128 v[156:159], v30 offset:28928
	ds_read_b128 v[160:163], v30 offset:29184
	ds_read_b128 v[164:167], v30 offset:29440
	ds_read_b32 v168, v31 offset:3584
	ds_read_b32 v169, v31 offset:3600
	v_add_f32_dpp v192, v192, v192 row_mirror row_mask:0xf bank_mask:0xf
	v_add_f32_dpp v194, v194, v194 row_mirror row_mask:0xf bank_mask:0xf
	v_pk_fma_f32 v[122:123], v[192:193], v[176:177], v[122:123] op_sel_hi:[0,1,1]
	v_pk_fma_f32 v[126:127], v[194:195], v[176:177], v[126:127] op_sel_hi:[0,1,1]
	v_pk_fma_f32 v[124:125], v[192:193], v[178:179], v[124:125] op_sel_hi:[0,1,1]
	v_pk_fma_f32 v[128:129], v[194:195], v[178:179], v[128:129] op_sel_hi:[0,1,1]
	s_waitcnt lgkmcnt(13)
	v_pk_mul_f32 v[192:193], v[122:123], v[132:133]
	v_pk_mul_f32 v[194:195], v[126:127], v[132:133]
	v_pk_mul_f32 v[196:197], v[122:123], v[184:185]
	v_pk_mul_f32 v[198:199], v[126:127], v[184:185]
	v_pk_fma_f32 v[192:193], v[124:125], v[134:135], v[192:193]
	v_pk_fma_f32 v[194:195], v[128:129], v[134:135], v[194:195]
	v_pk_fma_f32 v[196:197], v[124:125], v[186:187], v[196:197]
	v_pk_fma_f32 v[198:199], v[128:129], v[186:187], v[198:199]
	v_add_f32_e32 v192, v192, v193
	v_add_f32_e32 v194, v194, v195
	v_add_f32_e32 v196, v196, v197
	v_add_f32_e32 v198, v198, v199
	s_waitcnt lgkmcnt(8)
; __device__ __forceinline__ void scan_unit(const Args& A, LAS unsigned char* lds, int s, int tid) {
;     ...
;             for (int tl = 0; tl < SC_TC; ++tl) {
;                 float sa, yy;
;                 asm volatile(
;                     "v_mul_f32_e32 %0, %2, %6\n\t"
;                     "v_mul_f32_e32 %1, %2, %10\n\t"
;                     "v_fmac_f32_e32 %0, %3, %7\n\t"
;                     "v_fmac_f32_e32 %1, %3, %11\n\t"
;                     "v_fmac_f32_e32 %0, %4, %8\n\t"
;                     "v_fmac_f32_e32 %1, %4, %12\n\t"
;                     "v_fmac_f32_e32 %0, %5, %9\n\t"
;                     "v_fmac_f32_e32 %1, %5, %13\n\t"
;                     "v_fmac_f32_e32 %2, %18, %14\n\t"
;                     "v_add_f32_dpp %0, %0, %0 quad_perm:[1,0,3,2] row_mask:0xf bank_mask:0xf\n\t"
;                     "v_fmac_f32_e32 %3, %18, %15\n\t"
;                     "v_fmac_f32_e32 %4, %18, %16\n\t"
;                     "v_add_f32_dpp %0, %0, %0 quad_perm:[2,3,0,1] row_mask:0xf bank_mask:0xf\n\t"
;                     "v_fmac_f32_e32 %5, %18, %17\n\t"
;                     "s_nop 0\n\t"
;                     "v_add_f32_dpp %0, %0, %0 row_half_mirror row_mask:0xf bank_mask:0xf\n\t"
;                     : "=&v"(sa), "=&v"(yy), "+v"(S0), "+v"(S1), "+v"(S2), "+v"(S3)
;                     : "v"(a.x), "v"(a.y), "v"(a.z), "v"(a.w), "v"(pr.x), "v"(pr.y), "v"(pr.z), "v"(pr.w), "v"(k.x), "v"(k.y), "v"(k.z), "v"(k.w), "v"(v));
;                 if (tl > 0) yb[(tl - 1) * SC_YS + lane] = yy;
;                 const f32x4 b_now = bb; pr = r;
;                 a = a1; bb = bb1; k = k1; r = r1; v = v1;
;                 if (tl + 2 < SC_TC) { const LAS float* sn = st + (tl + 2) * SC_STEP_F;
;                     a1 = *(const LAS f32x4*)(sn); bb1 = *(const LAS f32x4*)(sn + 64); k1 = *(const LAS f32x4*)(sn + 128); r1 = *(const LAS f32x4*)(sn + 192); v1 = vp[(tl + 2) * 32]; }
;                 __builtin_amdgcn_sched_barrier(0);
;                 if (tl + 2 >= SC_TC) asm volatile("s_nop 1");
;                 asm volatile(
;                     "v_add_f32_dpp %4, %4, %4 row_mirror row_mask:0xf bank_mask:0xf\n\t"
;                     "v_fmac_f32_e32 %0, %4, %5\n\t"
;                     "v_fmac_f32_e32 %1, %4, %6\n\t"
;                     "v_fmac_f32_e32 %2, %4, %7\n\t"
;                     "v_fmac_f32_e32 %3, %4, %8\n\t"
	v_add_f32_dpp v192, v192, v192 quad_perm:[1,0,3,2] row_mask:0xf bank_mask:0xf
	v_add_f32_dpp v194, v194, v194 quad_perm:[1,0,3,2] row_mask:0xf bank_mask:0xf
	v_pk_fma_f32 v[122:123], v[148:149], v[140:141], v[122:123] op_sel_hi:[0,1,1]
	v_pk_fma_f32 v[126:127], v[148:149], v[140:141], v[126:127] op_sel:[1,0,0] op_sel_hi:[1,1,1]
	v_add_f32_dpp v192, v192, v192 quad_perm:[2,3,0,1] row_mask:0xf bank_mask:0xf
	v_add_f32_dpp v194, v194, v194 quad_perm:[2,3,0,1] row_mask:0xf bank_mask:0xf
	v_pk_fma_f32 v[124:125], v[148:149], v[142:143], v[124:125] op_sel_hi:[0,1,1]
	v_add_f32_dpp v192, v192, v192 row_half_mirror row_mask:0xf bank_mask:0xf
	v_add_f32_dpp v194, v194, v194 row_half_mirror row_mask:0xf bank_mask:0xf
	v_pk_fma_f32 v[128:129], v[148:149], v[142:143], v[128:129] op_sel:[1,0,0] op_sel_hi:[1,1,1]
	ds_write_b32 v204, v196 offset:7072
	ds_write_b32 v204, v198 offset:15776
	ds_read_b128 v[172:175], v30 offset:29696
	ds_read_b128 v[176:179], v30 offset:29952
	ds_read_b128 v[180:183], v30 offset:30208
	ds_read_b128 v[184:187], v30 offset:30464
	ds_read_b32 v188, v31 offset:3712
	ds_read_b32 v189, v31 offset:3728
	v_add_f32_dpp v192, v192, v192 row_mirror row_mask:0xf bank_mask:0xf
	v_add_f32_dpp v194, v194, v194 row_mirror row_mask:0xf bank_mask:0xf
	v_pk_fma_f32 v[122:123], v[192:193], v[136:137], v[122:123] op_sel_hi:[0,1,1]
	v_pk_fma_f32 v[126:127], v[194:195], v[136:137], v[126:127] op_sel_hi:[0,1,1]
	v_pk_fma_f32 v[124:125], v[192:193], v[138:139], v[124:125] op_sel_hi:[0,1,1]
	v_pk_fma_f32 v[128:129], v[194:195], v[138:139], v[128:129] op_sel_hi:[0,1,1]
	s_waitcnt lgkmcnt(13)
	v_pk_mul_f32 v[192:193], v[122:123], v[152:153]
	v_pk_mul_f32 v[194:195], v[126:127], v[152:153]
	v_pk_mul_f32 v[196:197], v[122:123], v[144:145]
	v_pk_mul_f32 v[198:199], v[126:127], v[144:145]
	v_pk_fma_f32 v[192:193], v[124:125], v[154:155], v[192:193]
	v_pk_fma_f32 v[194:195], v[128:129], v[154:155], v[194:195]
	v_pk_fma_f32 v[196:197], v[124:125], v[146:147], v[196:197]
	v_pk_fma_f32 v[198:199], v[128:129], v[146:147], v[198:199]
	v_add_f32_e32 v192, v192, v193
	v_add_f32_e32 v194, v194, v195
	v_add_f32_e32 v196, v196, v197
	v_add_f32_e32 v198, v198, v199
	s_waitcnt lgkmcnt(8)
	v_add_f32_dpp v192, v192, v192 quad_perm:[1,0,3,2] row_mask:0xf bank_mask:0xf
	v_add_f32_dpp v194, v194, v194 quad_perm:[1,0,3,2] row_mask:0xf bank_mask:0xf
	v_pk_fma_f32 v[122:123], v[168:169], v[160:161], v[122:123] op_sel_hi:[0,1,1]
	v_pk_fma_f32 v[126:127], v[168:169], v[160:161], v[126:127] op_sel:[1,0,0] op_sel_hi:[1,1,1]
	v_add_f32_dpp v192, v192, v192 quad_perm:[2,3,0,1] row_mask:0xf bank_mask:0xf
	v_add_f32_dpp v194, v194, v194 quad_perm:[2,3,0,1] row_mask:0xf bank_mask:0xf
	v_pk_fma_f32 v[124:125], v[168:169], v[162:163], v[124:125] op_sel_hi:[0,1,1]
	v_add_f32_dpp v192, v192, v192 row_half_mirror row_mask:0xf bank_mask:0xf
	v_add_f32_dpp v194, v194, v194 row_half_mirror row_mask:0xf bank_mask:0xf
	v_pk_fma_f32 v[128:129], v[168:169], v[162:163], v[128:129] op_sel:[1,0,0] op_sel_hi:[1,1,1]
	ds_write_b32 v204, v196 offset:7344
	ds_write_b32 v204, v198 offset:16048
	ds_read_b128 v[132:135], v30 offset:30720
	ds_read_b128 v[136:139], v30 offset:30976
	ds_read_b128 v[140:143], v30 offset:31232
	ds_read_b128 v[144:147], v30 offset:31488
	ds_read_b32 v148, v31 offset:3840
	ds_read_b32 v149, v31 offset:3856
	v_add_f32_dpp v192, v192, v192 row_mirror row_mask:0xf bank_mask:0xf
	v_add_f32_dpp v194, v194, v194 row_mirror row_mask:0xf bank_mask:0xf
	v_pk_fma_f32 v[122:123], v[192:193], v[156:157], v[122:123] op_sel_hi:[0,1,1]
	v_pk_fma_f32 v[126:127], v[194:195], v[156:157], v[126:127] op_sel_hi:[0,1,1]
	v_pk_fma_f32 v[124:125], v[192:193], v[158:159], v[124:125] op_sel_hi:[0,1,1]
	v_pk_fma_f32 v[128:129], v[194:195], v[158:159], v[128:129] op_sel_hi:[0,1,1]
	s_waitcnt lgkmcnt(13)
	v_pk_mul_f32 v[192:193], v[122:123], v[172:173]
	v_pk_mul_f32 v[194:195], v[126:127], v[172:173]
	v_pk_mul_f32 v[196:197], v[122:123], v[164:165]
	v_pk_mul_f32 v[198:199], v[126:127], v[164:165]
	v_pk_fma_f32 v[192:193], v[124:125], v[174:175], v[192:193]
	v_pk_fma_f32 v[194:195], v[128:129], v[174:175], v[194:195]
	v_pk_fma_f32 v[196:197], v[124:125], v[166:167], v[196:197]
	v_pk_fma_f32 v[198:199], v[128:129], v[166:167], v[198:199]
	v_add_f32_e32 v192, v192, v193
	v_add_f32_e32 v194, v194, v195
	v_add_f32_e32 v196, v196, v197
	v_add_f32_e32 v198, v198, v199
	s_waitcnt lgkmcnt(8)
	v_add_f32_dpp v192, v192, v192 quad_perm:[1,0,3,2] row_mask:0xf bank_mask:0xf
	v_add_f32_dpp v194, v194, v194 quad_perm:[1,0,3,2] row_mask:0xf bank_mask:0xf
	v_pk_fma_f32 v[122:123], v[188:189], v[180:181], v[122:123] op_sel_hi:[0,1,1]
	v_pk_fma_f32 v[126:127], v[188:189], v[180:181], v[126:127] op_sel:[1,0,0] op_sel_hi:[1,1,1]
	v_add_f32_dpp v192, v192, v192 quad_perm:[2,3,0,1] row_mask:0xf bank_mask:0xf
	v_add_f32_dpp v194, v194, v194 quad_perm:[2,3,0,1] row_mask:0xf bank_mask:0xf
	v_pk_fma_f32 v[124:125], v[188:189], v[182:183], v[124:125] op_sel_hi:[0,1,1]
	v_add_f32_dpp v192, v192, v192 row_half_mirror row_mask:0xf bank_mask:0xf
	v_add_f32_dpp v194, v194, v194 row_half_mirror row_mask:0xf bank_mask:0xf
	v_pk_fma_f32 v[128:129], v[188:189], v[182:183], v[128:129] op_sel:[1,0,0] op_sel_hi:[1,1,1]
	ds_write_b32 v204, v196 offset:7616
	ds_write_b32 v204, v198 offset:16320
	ds_read_b128 v[152:155], v30 offset:31744
	ds_read_b128 v[156:159], v30 offset:32000
	ds_read_b128 v[160:163], v30 offset:32256
	ds_read_b128 v[164:167], v30 offset:32512
	ds_read_b32 v168, v31 offset:3968
	ds_read_b32 v169, v31 offset:3984
	v_add_f32_dpp v192, v192, v192 row_mirror row_mask:0xf bank_mask:0xf
	v_add_f32_dpp v194, v194, v194 row_mirror row_mask:0xf bank_mask:0xf
	v_pk_fma_f32 v[122:123], v[192:193], v[176:177], v[122:123] op_sel_hi:[0,1,1]
	v_pk_fma_f32 v[126:127], v[194:195], v[176:177], v[126:127] op_sel_hi:[0,1,1]
	v_pk_fma_f32 v[124:125], v[192:193], v[178:179], v[124:125] op_sel_hi:[0,1,1]
	v_pk_fma_f32 v[128:129], v[194:195], v[178:179], v[128:129] op_sel_hi:[0,1,1]
	s_waitcnt lgkmcnt(13)
; #define LAS __attribute__((address_space(3)))
; __device__ __forceinline__ void scan_store(const ScanRegs& g, const ScanConst& K, const Args& A, LAS float* buf, int b, int h, int half, int c, int tid) {
;     const int jq = tid & 15, tl = tid >> 4, t = c * SC_TC + tl; const size_t m = (size_t)b * T + t;
;     const f32x4 mu_r = K.mu_r, mu_k = K.mu_k, kk_w = K.kk_w, ka_w = K.ka_w, rk_w = K.rk_w; const float mu_va = K.mu_va, mu_vb = K.mu_vb;
;     const f32x4 rs = g.r0 + (g.r1 - g.r0) * mu_r, ks = g.k0 + (g.k1 - g.k0) * mu_k;
;     f32x4 kk = ks * kk_w;
;     const float ss = row16_sum((kk.x * kk.x + kk.y * kk.y) + (kk.z * kk.z + kk.w * kk.w));
;     kk = kk * __builtin_amdgcn_rsqf(fmaxf(ss, 1e-24f));
;     const f32x4 km = ks * (1.0f + (g.al - 1.0f) * ka_w);
;     const f32x4 rkk = rs * km * rk_w;
;     const float cf = row16_sum((rkk.x + rkk.y) + (rkk.z + rkk.w));
;     if (half == 0 && jq == 0) ((float*)(A.ws + WS_COEF))[m * NH + h] = cf;
; __device__ __forceinline__ void scan_unit(const Args& A, LAS unsigned char* lds, int s, int tid) {
;     ...
;                 if (tl + 2 < SC_TC) { const LAS float* sn = st + (tl + 2) * SC_STEP_F;
;                     a1 = *(const LAS f32x4*)(sn); bb1 = *(const LAS f32x4*)(sn + 64); k1 = *(const LAS f32x4*)(sn + 128); r1 = *(const LAS f32x4*)(sn + 192); v1 = vp[(tl + 2) * 32]; }
;                 __builtin_amdgcn_sched_barrier(0);
;                 if (tl + 2 >= SC_TC) asm volatile("s_nop 1");
;                 asm volatile(
;                     "v_add_f32_dpp %4, %4, %4 row_mirror row_mask:0xf bank_mask:0xf\n\t"
;                     "v_fmac_f32_e32 %0, %4, %5\n\t"
;                     "v_fmac_f32_e32 %1, %4, %6\n\t"
;                     "v_fmac_f32_e32 %2, %4, %7\n\t"
;                     "v_fmac_f32_e32 %3, %4, %8\n\t"
;                     : "+v"(S0), "+v"(S1), "+v"(S2), "+v"(S3), "+v"(sa)
;                     : "v"(b_now.x), "v"(b_now.y), "v"(b_now.z), "v"(b_now.w));
;             }
;             { float yy = sc_mul(S0, pr.x); yy = sc_fma(S1, pr.y, yy); yy = sc_fma(S2, pr.z, yy); yy = sc_fma(S3, pr.w, yy); yb[(SC_TC - 1) * SC_YS + lane] = yy; }
;             { const f32x4 ge = *(const LAS f32x4*)(cur + SC_G_OFF + 4 * jq); S0 = sc_mul(S0, ge.x); S1 = sc_mul(S1, ge.y); S2 = sc_mul(S2, ge.z); S3 = sc_mul(S3, ge.w); }
	v_pk_mul_f32 v[192:193], v[122:123], v[132:133]
	v_pk_mul_f32 v[194:195], v[126:127], v[132:133]
	v_pk_mul_f32 v[196:197], v[122:123], v[184:185]
	v_pk_mul_f32 v[198:199], v[126:127], v[184:185]
	v_pk_fma_f32 v[192:193], v[124:125], v[134:135], v[192:193]
	v_pk_fma_f32 v[194:195], v[128:129], v[134:135], v[194:195]
	v_pk_fma_f32 v[196:197], v[124:125], v[186:187], v[196:197]
	v_pk_fma_f32 v[198:199], v[128:129], v[186:187], v[198:199]
	v_add_f32_e32 v192, v192, v193
	v_add_f32_e32 v194, v194, v195
	v_add_f32_e32 v196, v196, v197
	v_add_f32_e32 v198, v198, v199
	s_waitcnt lgkmcnt(8)
	v_add_f32_dpp v192, v192, v192 quad_perm:[1,0,3,2] row_mask:0xf bank_mask:0xf
	v_add_f32_dpp v194, v194, v194 quad_perm:[1,0,3,2] row_mask:0xf bank_mask:0xf
	v_pk_fma_f32 v[122:123], v[148:149], v[140:141], v[122:123] op_sel_hi:[0,1,1]
	v_pk_fma_f32 v[126:127], v[148:149], v[140:141], v[126:127] op_sel:[1,0,0] op_sel_hi:[1,1,1]
	v_add_f32_dpp v192, v192, v192 quad_perm:[2,3,0,1] row_mask:0xf bank_mask:0xf
	v_add_f32_dpp v194, v194, v194 quad_perm:[2,3,0,1] row_mask:0xf bank_mask:0xf
	v_pk_fma_f32 v[124:125], v[148:149], v[142:143], v[124:125] op_sel_hi:[0,1,1]
	v_add_f32_dpp v192, v192, v192 row_half_mirror row_mask:0xf bank_mask:0xf
	v_add_f32_dpp v194, v194, v194 row_half_mirror row_mask:0xf bank_mask:0xf
	v_pk_fma_f32 v[128:129], v[148:149], v[142:143], v[128:129] op_sel:[1,0,0] op_sel_hi:[1,1,1]
	ds_write_b32 v204, v196 offset:7888
	ds_write_b32 v204, v198 offset:16592
	v_add_f32_dpp v192, v192, v192 row_mirror row_mask:0xf bank_mask:0xf
	v_add_f32_dpp v194, v194, v194 row_mirror row_mask:0xf bank_mask:0xf
	v_pk_fma_f32 v[122:123], v[192:193], v[136:137], v[122:123] op_sel_hi:[0,1,1]
	v_pk_fma_f32 v[126:127], v[194:195], v[136:137], v[126:127] op_sel_hi:[0,1,1]
	v_pk_fma_f32 v[124:125], v[192:193], v[138:139], v[124:125] op_sel_hi:[0,1,1]
	v_pk_fma_f32 v[128:129], v[194:195], v[138:139], v[128:129] op_sel_hi:[0,1,1]
	s_waitcnt lgkmcnt(7)
	v_pk_mul_f32 v[192:193], v[122:123], v[152:153]
	v_pk_mul_f32 v[194:195], v[126:127], v[152:153]
	v_pk_mul_f32 v[196:197], v[122:123], v[144:145]
	v_pk_mul_f32 v[198:199], v[126:127], v[144:145]
	v_pk_fma_f32 v[192:193], v[124:125], v[154:155], v[192:193]
	v_pk_fma_f32 v[194:195], v[128:129], v[154:155], v[194:195]
	v_pk_fma_f32 v[196:197], v[124:125], v[146:147], v[196:197]
	v_pk_fma_f32 v[198:199], v[128:129], v[146:147], v[198:199]
	v_add_f32_e32 v192, v192, v193
	v_add_f32_e32 v194, v194, v195
	v_add_f32_e32 v196, v196, v197
	v_add_f32_e32 v198, v198, v199
	s_waitcnt lgkmcnt(2)
	v_add_f32_dpp v192, v192, v192 quad_perm:[1,0,3,2] row_mask:0xf bank_mask:0xf
	v_add_f32_dpp v194, v194, v194 quad_perm:[1,0,3,2] row_mask:0xf bank_mask:0xf
	v_pk_fma_f32 v[122:123], v[168:169], v[160:161], v[122:123] op_sel_hi:[0,1,1]
	v_pk_fma_f32 v[126:127], v[168:169], v[160:161], v[126:127] op_sel:[1,0,0] op_sel_hi:[1,1,1]
	v_add_f32_dpp v192, v192, v192 quad_perm:[2,3,0,1] row_mask:0xf bank_mask:0xf
	v_add_f32_dpp v194, v194, v194 quad_perm:[2,3,0,1] row_mask:0xf bank_mask:0xf
	v_pk_fma_f32 v[124:125], v[168:169], v[162:163], v[124:125] op_sel_hi:[0,1,1]
	v_add_f32_dpp v192, v192, v192 row_half_mirror row_mask:0xf bank_mask:0xf
	v_add_f32_dpp v194, v194, v194 row_half_mirror row_mask:0xf bank_mask:0xf
	v_pk_fma_f32 v[128:129], v[168:169], v[162:163], v[128:129] op_sel:[1,0,0] op_sel_hi:[1,1,1]
	ds_write_b32 v204, v196 offset:8160
	ds_write_b32 v204, v198 offset:16864
	v_add_f32_dpp v192, v192, v192 row_mirror row_mask:0xf bank_mask:0xf
	v_add_f32_dpp v194, v194, v194 row_mirror row_mask:0xf bank_mask:0xf
	v_pk_fma_f32 v[122:123], v[192:193], v[156:157], v[122:123] op_sel_hi:[0,1,1]
	v_pk_fma_f32 v[126:127], v[194:195], v[156:157], v[126:127] op_sel_hi:[0,1,1]
	v_pk_fma_f32 v[124:125], v[192:193], v[158:159], v[124:125] op_sel_hi:[0,1,1]
	v_pk_fma_f32 v[128:129], v[194:195], v[158:159], v[128:129] op_sel_hi:[0,1,1]
	v_add_u32_e32 v30, s0, v71
	ds_read_b128 v[200:203], v30
	v_pk_mul_f32 v[196:197], v[122:123], v[164:165]
	v_pk_mul_f32 v[198:199], v[126:127], v[164:165]
	v_pk_fma_f32 v[196:197], v[124:125], v[166:167], v[196:197]
	v_pk_fma_f32 v[198:199], v[128:129], v[166:167], v[198:199]
	v_add_f32_e32 v196, v196, v197
	v_add_f32_e32 v198, v198, v199
	ds_write_b32 v204, v196 offset:8432
	ds_write_b32 v204, v198 offset:17136
	s_waitcnt lgkmcnt(2)
	v_pk_mul_f32 v[122:123], v[122:123], v[200:201]
	v_pk_mul_f32 v[126:127], v[126:127], v[200:201]
	v_pk_mul_f32 v[124:125], v[124:125], v[202:203]
	v_pk_mul_f32 v[128:129], v[128:129], v[202:203]
.Lsc2_skip:
	s_andn2_b64 vcc, exec, s[20:21]
	s_cbranch_vccnz .LBB0_499
	s_waitcnt vmcnt(6)
	v_sub_f32_e32 v53, v33, v21
	v_sub_f32_e32 v52, v32, v20
	v_pk_fma_f32 v[64:65], v[0:1], v[52:53], v[20:21]
	s_waitcnt vmcnt(5)
	v_sub_f32_e32 v53, v39, v27
	v_sub_f32_e32 v52, v38, v26
	v_sub_f32_e32 v55, v37, v25
	v_sub_f32_e32 v54, v36, v24
	v_pk_fma_f32 v[68:69], v[16:17], v[54:55], v[24:25]
	v_pk_fma_f32 v[66:67], v[18:19], v[52:53], v[26:27]
	v_pk_mul_f32 v[54:55], v[4:5], v[68:69]
	v_pk_mul_f32 v[52:53], v[6:7], v[66:67]
	v_pk_mul_f32 v[90:91], v[54:55], v[54:55]
	v_pk_mul_f32 v[88:89], v[52:53], v[52:53]
	v_sub_f32_e32 v31, v35, v23
	v_pk_mov_b32 v[92:93], v[90:91], v[88:89] op_sel:[1,0]
	v_mov_b32_e32 v91, v89
	v_pk_add_f32 v[88:89], v[92:93], v[90:91]
	s_waitcnt vmcnt(3)
	v_pk_add_f32 v[90:91], v[46:47], -1.0 op_sel_hi:[1,0]
	v_pk_add_f32 v[92:93], v[44:45], -1.0 op_sel_hi:[1,0]
	v_sub_f32_e32 v30, v34, v22
	v_pk_fma_f32 v[90:91], v[10:11], v[90:91], 1.0 op_sel_hi:[1,1,0]
	v_pk_fma_f32 v[92:93], v[8:9], v[92:93], 1.0 op_sel_hi:[1,1,0]
	v_pk_fma_f32 v[30:31], v[2:3], v[30:31], v[22:23]
	v_pk_mul_f32 v[66:67], v[66:67], v[90:91]
	v_pk_mul_f32 v[68:69], v[68:69], v[92:93]
	v_pk_mul_f32 v[92:93], v[30:31], v[66:67]
	v_pk_mul_f32 v[90:91], v[64:65], v[68:69]
	v_pk_mul_f32 v[92:93], v[14:15], v[92:93]
	v_pk_mul_f32 v[90:91], v[12:13], v[90:91]
	v_add_f32_e32 v87, v88, v89
	v_add_f32_e32 v89, v90, v91
	v_add_f32_e32 v90, v92, v93
	v_add_f32_e32 v89, v89, v90
	v_add_f32_dpp v87, v87, v87 quad_perm:[1,0,3,2] row_mask:0xf bank_mask:0xf bound_ctrl:1
	v_mov_b32_e32 v88, 0
	v_add_f32_dpp v89, v89, v89 quad_perm:[1,0,3,2] row_mask:0xf bank_mask:0xf bound_ctrl:1
	v_add_f32_dpp v87, v87, v87 quad_perm:[2,3,0,1] row_mask:0xf bank_mask:0xf bound_ctrl:1
	v_mov_b32_e32 v90, 0
	v_add_f32_dpp v89, v89, v89 quad_perm:[2,3,0,1] row_mask:0xf bank_mask:0xf bound_ctrl:1
	v_add_f32_dpp v87, v87, v87 row_half_mirror row_mask:0xf bank_mask:0xf bound_ctrl:1
	s_nop 0
	v_add_f32_dpp v89, v89, v89 row_half_mirror row_mask:0xf bank_mask:0xf bound_ctrl:1
	v_mov_b32_dpp v88, v87 row_mirror row_mask:0xf bank_mask:0xf
	s_nop 0
	v_mov_b32_dpp v90, v89 row_mirror row_mask:0xf bank_mask:0xf
	s_and_saveexec_b64 s[20:21], s[2:3]
	s_cbranch_execz .LBB0_509
	v_add_f32_e32 v89, v89, v90
	global_store_dword v[58:59], v89, off
